# speedup vs baseline: 1.0004x; 1.0004x over previous
.LBB0_175:
	s_cmpk_eq_i32 s2, 0x780
	s_mov_b32 s4, 0x10000
	s_cbranch_scc1 .LBB0_174
	s_and_b32 s4, s1, 0x10000
	s_xor_b32 s5, s4, 0x10000
	s_add_i32 s5, s31, s5
	s_add_i32 s6, s5, 0x8000
	v_add_u32_e32 v199, s4, v197
	v_add_u32_e32 v0, s4, v196
	ds_read_b128 v[172:175], v199 offset:32768
	ds_read_b128 v[176:179], v199 offset:34816
	ds_read_b128 v[180:183], v199 offset:36864
	ds_read_b128 v[184:187], v199 offset:38912
	ds_read_b128 v[188:191], v0
	ds_read_b128 v[200:203], v0 offset:2048
	v_add_u32_e32 v228, v0, v195
	ds_read_b128 v[204:207], v0 offset:4096
	ds_read_b128 v[208:211], v0 offset:6144
	v_lshl_add_u64 v[252:253], v[114:115], 0, s[2:3]
	s_mov_b32 m0, s5
	s_nop 0
	global_load_lds_dwordx4 v[252:253], off
	v_lshl_add_u64 v[252:253], v[126:127], 0, s[2:3]
	s_mov_b32 m0, s6
	s_nop 0
	global_load_lds_dwordx4 v[252:253], off
	s_waitcnt lgkmcnt(0)
	v_mfma_f32_16x16x32_bf16 v[142:145], v[172:175], v[188:191], v[142:145]
	v_mfma_f32_16x16x32_bf16 v[138:141], v[176:179], v[188:191], v[138:141]
	v_lshl_add_u64 v[252:253], v[116:117], 0, s[2:3]
	s_add_i32 m0, s5, 0x2000
	s_nop 0
	global_load_lds_dwordx4 v[252:253], off
	v_mfma_f32_16x16x32_bf16 v[130:133], v[180:183], v[188:191], v[130:133]
	v_mfma_f32_16x16x32_bf16 v[118:121], v[184:187], v[188:191], v[118:121]
	v_mfma_f32_16x16x32_bf16 v[110:113], v[172:175], v[200:203], v[110:113]
	v_mfma_f32_16x16x32_bf16 v[106:109], v[176:179], v[200:203], v[106:109]
	v_lshl_add_u64 v[252:253], v[128:129], 0, s[2:3]
	s_add_i32 m0, s5, 0xa000
	s_nop 0
	global_load_lds_dwordx4 v[252:253], off
	v_mfma_f32_16x16x32_bf16 v[102:105], v[180:183], v[200:203], v[102:105]
	v_mfma_f32_16x16x32_bf16 v[98:101], v[184:187], v[200:203], v[98:101]
	ds_read_b128 v[188:191], v0 offset:8192
	ds_read_b128 v[200:203], v0 offset:10240
	v_mfma_f32_16x16x32_bf16 v[94:97], v[172:175], v[204:207], v[94:97]
	v_mfma_f32_16x16x32_bf16 v[90:93], v[176:179], v[204:207], v[90:93]
	v_lshl_add_u64 v[252:253], v[122:123], 0, s[2:3]
	s_add_i32 m0, s5, 0x4000
	s_nop 0
	global_load_lds_dwordx4 v[252:253], off
	v_mfma_f32_16x16x32_bf16 v[86:89], v[180:183], v[204:207], v[86:89]
	v_mfma_f32_16x16x32_bf16 v[82:85], v[184:187], v[204:207], v[82:85]
	v_mfma_f32_16x16x32_bf16 v[78:81], v[172:175], v[208:211], v[78:81]
	v_mfma_f32_16x16x32_bf16 v[74:77], v[176:179], v[208:211], v[74:77]
	v_lshl_add_u64 v[252:253], v[134:135], 0, s[2:3]
	s_add_i32 m0, s5, 0xc000
	s_nop 0
	global_load_lds_dwordx4 v[252:253], off
	v_mfma_f32_16x16x32_bf16 v[70:73], v[180:183], v[208:211], v[70:73]
	v_mfma_f32_16x16x32_bf16 v[66:69], v[184:187], v[208:211], v[66:69]
	ds_read_b128 v[204:207], v0 offset:12288
	ds_read_b128 v[208:211], v0 offset:14336
	s_waitcnt lgkmcnt(0)
	v_mfma_f32_16x16x32_bf16 v[62:65], v[172:175], v[188:191], v[62:65]
	v_add_u32_e32 v0, v199, v195
	v_mfma_f32_16x16x32_bf16 v[58:61], v[176:179], v[188:191], v[58:61]
	v_lshl_add_u64 v[252:253], v[124:125], 0, s[2:3]
	s_add_i32 m0, s5, 0x6000
	s_nop 0
	global_load_lds_dwordx4 v[252:253], off
	v_mfma_f32_16x16x32_bf16 v[54:57], v[180:183], v[188:191], v[54:57]
	v_mfma_f32_16x16x32_bf16 v[50:53], v[184:187], v[188:191], v[50:53]
	v_mfma_f32_16x16x32_bf16 v[46:49], v[172:175], v[200:203], v[46:49]
	v_mfma_f32_16x16x32_bf16 v[42:45], v[176:179], v[200:203], v[42:45]
	v_lshl_add_u64 v[252:253], v[136:137], 0, s[2:3]
	s_add_i32 m0, s5, 0xe000
	s_nop 0
	global_load_lds_dwordx4 v[252:253], off
	v_mfma_f32_16x16x32_bf16 v[38:41], v[180:183], v[200:203], v[38:41]
	v_mfma_f32_16x16x32_bf16 v[34:37], v[184:187], v[200:203], v[34:37]
	ds_read_b128 v[188:191], v0 offset:32768
	ds_read_b128 v[200:203], v0 offset:34816
	ds_read_b128 v[212:215], v0 offset:36864
	ds_read_b128 v[216:219], v0 offset:38912
	ds_read_b128 v[220:223], v228
	ds_read_b128 v[224:227], v228 offset:2048
	v_mfma_f32_16x16x32_bf16 v[30:33], v[172:175], v[204:207], v[30:33]
	v_mfma_f32_16x16x32_bf16 v[26:29], v[176:179], v[204:207], v[26:29]
	v_mfma_f32_16x16x32_bf16 v[22:25], v[180:183], v[204:207], v[22:25]
	v_mfma_f32_16x16x32_bf16 v[18:21], v[184:187], v[204:207], v[18:21]
	v_mfma_f32_16x16x32_bf16 v[14:17], v[172:175], v[208:211], v[14:17]
	v_mfma_f32_16x16x32_bf16 v[10:13], v[176:179], v[208:211], v[10:13]
	v_mfma_f32_16x16x32_bf16 v[6:9], v[180:183], v[208:211], v[6:9]
	v_mfma_f32_16x16x32_bf16 v[2:5], v[184:187], v[208:211], v[2:5]
	ds_read_b128 v[172:175], v228 offset:4096
	ds_read_b128 v[176:179], v228 offset:6144
	s_waitcnt lgkmcnt(0)
	v_mfma_f32_16x16x32_bf16 v[142:145], v[188:191], v[220:223], v[142:145]
	v_mfma_f32_16x16x32_bf16 v[138:141], v[200:203], v[220:223], v[138:141]
	v_mfma_f32_16x16x32_bf16 v[130:133], v[212:215], v[220:223], v[130:133]
	v_mfma_f32_16x16x32_bf16 v[118:121], v[216:219], v[220:223], v[118:121]
	v_mfma_f32_16x16x32_bf16 v[110:113], v[188:191], v[224:227], v[110:113]
	v_mfma_f32_16x16x32_bf16 v[106:109], v[200:203], v[224:227], v[106:109]
	v_mfma_f32_16x16x32_bf16 v[102:105], v[212:215], v[224:227], v[102:105]
	v_mfma_f32_16x16x32_bf16 v[98:101], v[216:219], v[224:227], v[98:101]
	ds_read_b128 v[180:183], v228 offset:8192
	ds_read_b128 v[184:187], v228 offset:10240
	v_mfma_f32_16x16x32_bf16 v[94:97], v[188:191], v[172:175], v[94:97]
	v_mfma_f32_16x16x32_bf16 v[90:93], v[200:203], v[172:175], v[90:93]
	v_mfma_f32_16x16x32_bf16 v[86:89], v[212:215], v[172:175], v[86:89]
	v_mfma_f32_16x16x32_bf16 v[82:85], v[216:219], v[172:175], v[82:85]
	v_mfma_f32_16x16x32_bf16 v[78:81], v[188:191], v[176:179], v[78:81]
	v_mfma_f32_16x16x32_bf16 v[74:77], v[200:203], v[176:179], v[74:77]
	v_mfma_f32_16x16x32_bf16 v[70:73], v[212:215], v[176:179], v[70:73]
	v_mfma_f32_16x16x32_bf16 v[66:69], v[216:219], v[176:179], v[66:69]
	ds_read_b128 v[172:175], v228 offset:12288
	ds_read_b128 v[176:179], v228 offset:14336
	s_waitcnt lgkmcnt(0)
	v_mfma_f32_16x16x32_bf16 v[62:65], v[188:191], v[180:183], v[62:65]
	v_mfma_f32_16x16x32_bf16 v[58:61], v[200:203], v[180:183], v[58:61]
	v_mfma_f32_16x16x32_bf16 v[54:57], v[212:215], v[180:183], v[54:57]
	v_mfma_f32_16x16x32_bf16 v[50:53], v[216:219], v[180:183], v[50:53]
	v_mfma_f32_16x16x32_bf16 v[46:49], v[188:191], v[184:187], v[46:49]
	v_mfma_f32_16x16x32_bf16 v[42:45], v[200:203], v[184:187], v[42:45]
	v_mfma_f32_16x16x32_bf16 v[38:41], v[212:215], v[184:187], v[38:41]
	v_mfma_f32_16x16x32_bf16 v[34:37], v[216:219], v[184:187], v[34:37]
	v_mfma_f32_16x16x32_bf16 v[30:33], v[188:191], v[172:175], v[30:33]
	v_mfma_f32_16x16x32_bf16 v[26:29], v[200:203], v[172:175], v[26:29]
	v_mfma_f32_16x16x32_bf16 v[22:25], v[212:215], v[172:175], v[22:25]
	v_mfma_f32_16x16x32_bf16 v[18:21], v[216:219], v[172:175], v[18:21]
	v_mfma_f32_16x16x32_bf16 v[14:17], v[188:191], v[176:179], v[14:17]
	v_mfma_f32_16x16x32_bf16 v[10:13], v[200:203], v[176:179], v[10:13]
	v_mfma_f32_16x16x32_bf16 v[6:9], v[212:215], v[176:179], v[6:9]
	v_mfma_f32_16x16x32_bf16 v[2:5], v[216:219], v[176:179], v[2:5]
	s_add_i32 s1, s1, 0x10000
	s_waitcnt vmcnt(0)
	s_add_u32 s2, s2, 0x80
	s_addc_u32 s3, s3, 0
	s_cmpk_eq_i32 s2, 0x800
	s_waitcnt vmcnt(0)
	s_barrier
	s_cbranch_scc1 .LBB0_177
	s_branch .LBB0_175

; __device__ __forceinline__ void partialSM(f32x16& p0, f32x16& p1, float& m_reg, float& mn, float& alpha) {
;   constexpr float C = SCALE * 1.4426950408889634f;
;   float pmax = p0[0];
; #pragma unroll
;   for (int r = 1; r < 16; ++r) pmax = fmaxf(pmax, p0[r]);
; #pragma unroll
;   for (int r = 0; r < 16; ++r) pmax = fmaxf(pmax, p1[r]);
;   { auto rr = __builtin_amdgcn_permlane32_swap(__float_as_uint(pmax), __float_as_uint(pmax), false, false);
;     pmax = fmaxf(__uint_as_float(rr[0]), __uint_as_float(rr[1])); }
;   if (__builtin_expect(__all(pmax - m_reg <= THR / SCALE), 1)) { mn = m_reg; alpha = 1.f; }
; __device__ __forceinline__ void na_items(const Params& p, int l, int L, char* shm, const int tid, const int local, const int G, const int nNA) {
;     ...
;       const int kr = kr_lo + j;
;       const bool active = (kr >= r0w) && (kr < r0w + 8);
;       if (active) {
;         const char* Kc = Kl + cur * 8192; const char* Vc = Vl + cur * 8192;
;         f32x16 p0, p1;
; #pragma unroll
;         for (int r = 0; r < 16; ++r) { p0[r] = 0.f; p1[r] = 0.f; }
; #pragma unroll
;         for (int d0 = 0; d0 < 4; ++d0) {
;           bf16x8 b0 = *(const bf16x8*)(Kc + roff[d0]);
;           bf16x8 b1 = *(const bf16x8*)(Kc + roff[d0] + 4096);
;           p0 = __builtin_amdgcn_mfma_f32_32x32x16_bf16(b0, qr[d0], p0, 0, 0, 0);
;           p1 = __builtin_amdgcn_mfma_f32_32x32x16_bf16(b1, qr[d0], p1, 0, 0, 0);
;         }
;         {
;           const float* rb = rpbL + (kr - rq + 7) * 31 + (15 - qc);
; #pragma unroll
;           for (int r = 0; r < 16; ++r) {
;             const int kc = crow(r, hi);
;             const bool v0 = (kc >= c0) && (kc < c0 + 16);
;             const float b0 = rb[v0 ? kc : qc];
;             p0[r] = v0 ? p0[r] + b0 : -1e30f;
;             const int kc1 = kc + 32;
;             const bool v1 = (kc1 >= c0) && (kc1 < c0 + 16);
;             const float b1 = rb[v1 ? kc1 : qc];
;             p1[r] = v1 ? p1[r] + b1 : -1e30f;
;           }
;         }
;         float mn, alpha;
;         partialSM(p0, p1, m_reg, mn, alpha);
;         if (__any(alpha < 1.f)) {
;           if (hi == 0) wsf[r32] = alpha;
;           asm volatile("s_waitcnt lgkmcnt(0)" ::: "memory");
; #pragma unroll
;           for (int r = 0; r < 16; ++r) { const float a = wsf[crow(r, hi)]; o0[r] *= a; o1[r] *= a; }
;         }
.LBB0_447:
	s_and_b32 s97, s42, 1
	s_add_i32 s6, s99, s42
	s_cmp_ge_i32 s6, s46
	s_cselect_b64 s[42:43], -1, 0
	s_cmp_lt_i32 s6, s98
	s_cselect_b64 vcc, -1, 0
	s_and_b64 s[42:43], s[42:43], vcc
	s_andn2_b64 vcc, exec, s[42:43]
	s_cbranch_vccnz .LBB0_517
	s_lshl_b32 s6, s97, 13
	v_add_u32_e32 v236, s6, v109
	v_add_u32_e32 v237, s6, v120
	v_add_u32_e32 v240, s6, v121
	v_add_u32_e32 v241, s6, v122
	ds_read_b128 v[220:223], v236
	ds_read_b128 v[224:227], v236 offset:4096
	ds_read_b128 v[228:231], v237
	ds_read_b128 v[232:235], v237 offset:4096
	ds_read2_b32 v[2:3], v117 offset1:1
	ds_read2_b32 v[4:5], v117 offset0:2 offset1:3
	ds_read2_b32 v[6:7], v117 offset0:8 offset1:9
	ds_read2_b32 v[8:9], v117 offset0:10 offset1:11
	ds_read2_b32 v[10:11], v117 offset0:16 offset1:17
	ds_read2_b32 v[12:13], v117 offset0:18 offset1:19
	ds_read2_b32 v[250:251], v117 offset0:24 offset1:25
	ds_read2_b32 v[252:253], v117 offset0:26 offset1:27
	v_mov_b32_e32 v244, 0xf149f2ca
	s_waitcnt lgkmcnt(11)
	v_mfma_f32_32x32x16_bf16 v[64:79], v[220:223], v[80:83], 0
	ds_read_b128 v[220:223], v240
	s_waitcnt lgkmcnt(11)
	v_mfma_f32_32x32x16_bf16 v[48:63], v[224:227], v[80:83], 0
	ds_read_b128 v[224:227], v240 offset:4096
	s_waitcnt lgkmcnt(11)
	v_mfma_f32_32x32x16_bf16 v[64:79], v[228:231], v[84:87], v[64:79]
	ds_read_b128 v[228:231], v241
	s_waitcnt lgkmcnt(11)
	v_mfma_f32_32x32x16_bf16 v[48:63], v[232:235], v[84:87], v[48:63]
	ds_read_b128 v[232:235], v241 offset:4096
	s_waitcnt lgkmcnt(3)
	v_mfma_f32_32x32x16_bf16 v[64:79], v[220:223], v[88:91], v[64:79]
	s_waitcnt lgkmcnt(2)
	v_mfma_f32_32x32x16_bf16 v[48:63], v[224:227], v[88:91], v[48:63]
	s_waitcnt lgkmcnt(1)
	v_mfma_f32_32x32x16_bf16 v[64:79], v[228:231], v[92:95], v[64:79]
	s_waitcnt lgkmcnt(0)
	v_mfma_f32_32x32x16_bf16 v[48:63], v[232:235], v[92:95], v[48:63]
	s_nop 9
	v_add_f32_e32 v64, v64, v2
	v_add_f32_e32 v65, v65, v3
	v_add_f32_e32 v66, v66, v4
	v_add_f32_e32 v67, v67, v5
	v_add_f32_e32 v68, v68, v6
	v_add_f32_e32 v69, v69, v7
	v_add_f32_e32 v70, v70, v8
	v_add_f32_e32 v71, v71, v9
	v_add_f32_e32 v72, v72, v10
	v_add_f32_e32 v73, v73, v11
	v_add_f32_e32 v74, v74, v12
	v_add_f32_e32 v75, v75, v13
	v_add_f32_e32 v76, v76, v250
	v_add_f32_e32 v77, v77, v251
	v_add_f32_e32 v78, v78, v252
	v_add_f32_e32 v79, v79, v253
	ds_read2_b32 v[2:3], v117 offset0:32 offset1:33
	ds_read2_b32 v[4:5], v117 offset0:34 offset1:35
	ds_read2_b32 v[6:7], v117 offset0:40 offset1:41
	ds_read2_b32 v[8:9], v117 offset0:42 offset1:43
	ds_read2_b32 v[10:11], v117 offset0:48 offset1:49
	ds_read2_b32 v[12:13], v117 offset0:50 offset1:51
	ds_read2_b32 v[250:251], v117 offset0:56 offset1:57
	ds_read2_b32 v[252:253], v117 offset0:58 offset1:59
	v_cndmask_b32_e64 v64, v244, v64, s[8:9]
	v_cndmask_b32_e64 v65, v244, v65, s[10:11]
	v_cndmask_b32_e64 v66, v244, v66, s[12:13]
	v_cndmask_b32_e64 v67, v244, v67, s[14:15]
	v_cndmask_b32_e64 v68, v244, v68, s[16:17]
	v_cndmask_b32_e64 v69, v244, v69, s[18:19]
	v_cndmask_b32_e64 v70, v244, v70, s[20:21]
	v_cndmask_b32_e64 v71, v244, v71, s[22:23]
	v_cndmask_b32_e64 v72, v244, v72, s[66:67]
	v_cndmask_b32_e64 v73, v244, v73, s[68:69]
	v_cndmask_b32_e64 v74, v244, v74, s[72:73]
	v_cndmask_b32_e64 v75, v244, v75, s[74:75]
	v_cndmask_b32_e64 v76, v244, v76, s[78:79]
	v_cndmask_b32_e64 v77, v244, v77, s[0:1]
	v_cndmask_b32_e64 v78, v244, v78, s[70:71]
	v_cndmask_b32_e64 v79, v244, v79, s[2:3]
	s_waitcnt lgkmcnt(0)
	v_add_f32_e32 v48, v48, v2
	v_add_f32_e32 v49, v49, v3
	v_add_f32_e32 v50, v50, v4
	v_add_f32_e32 v51, v51, v5
	v_add_f32_e32 v52, v52, v6
	v_add_f32_e32 v53, v53, v7
	v_add_f32_e32 v54, v54, v8
	v_add_f32_e32 v55, v55, v9
	v_add_f32_e32 v56, v56, v10
	v_add_f32_e32 v57, v57, v11
	v_add_f32_e32 v58, v58, v12
	v_add_f32_e32 v59, v59, v13
	v_add_f32_e32 v60, v60, v250
	v_add_f32_e32 v61, v61, v251
	v_add_f32_e32 v62, v62, v252
	v_add_f32_e32 v63, v63, v253
	ds_read_b128 v[2:5], v236 offset:16384
	ds_read_b128 v[6:9], v236 offset:20480
	ds_read_b128 v[10:13], v237 offset:16384
	ds_read_b128 v[250:253], v237 offset:20480
	v_cndmask_b32_e64 v48, v244, v48, s[90:91]
	v_cndmask_b32_e64 v49, v244, v49, s[94:95]
	v_cndmask_b32_e64 v50, v244, v50, s[44:45]
	v_cndmask_b32_e64 v51, v244, v51, s[84:85]
	v_cndmask_b32_e64 v52, v244, v52, s[86:87]
	v_cndmask_b32_e64 v53, v244, v53, s[56:57]
	v_cndmask_b32_e64 v54, v244, v54, s[62:63]
	v_cndmask_b32_e64 v55, v244, v55, s[64:65]
	v_cndmask_b32_e64 v56, v244, v56, s[24:25]
	v_cndmask_b32_e64 v57, v244, v57, s[26:27]
	v_cndmask_b32_e64 v58, v244, v58, s[28:29]
	v_cndmask_b32_e64 v59, v244, v59, s[30:31]
	v_cndmask_b32_e64 v60, v244, v60, s[34:35]
	v_cndmask_b32_e64 v61, v244, v61, s[36:37]
	v_cndmask_b32_e64 v62, v244, v62, s[38:39]
	v_cndmask_b32_e64 v63, v244, v63, s[40:41]
	v_max3_f32 v245, v64, v65, v66
	v_max3_f32 v245, v245, v67, v68
	v_max3_f32 v245, v245, v69, v70
	v_max3_f32 v245, v245, v71, v72
	v_max3_f32 v245, v245, v73, v74
	v_max3_f32 v245, v245, v75, v76
	v_max3_f32 v245, v245, v77, v78
	v_max3_f32 v245, v245, v79, v48
	v_max3_f32 v245, v245, v49, v50
	v_max3_f32 v245, v245, v51, v52
	v_max3_f32 v245, v245, v53, v54
	v_max3_f32 v245, v245, v55, v56
	v_max3_f32 v245, v245, v57, v58
	v_max3_f32 v245, v245, v59, v60
	v_max3_f32 v245, v245, v61, v62
	v_max_f32_e32 v245, v245, v63
	v_mov_b32_e32 v238, v245
	s_nop 1
	v_permlane32_swap_b32_e32 v245, v238
	v_max_f32_e32 v245, v245, v238
	v_sub_f32_e32 v238, v245, v210
	s_mov_b32 s6, 0x42800000
	v_cmp_ge_f32_e32 vcc, s6, v238
	v_max_f32_e32 v238, v210, v245
	v_sub_f32_e32 v243, v210, v238
	v_mul_f32_e32 v243, 0x3e38aa3b, v243
	v_exp_f32_e32 v243, v243
	s_cmp_eq_u64 vcc, exec
	s_cselect_b64 s[42:43], -1, 0
	v_cndmask_b32_e64 v243, v243, 1.0, s[42:43]
	v_cmp_gt_f32_e32 vcc, 1.0, v243
	s_cbranch_vccz .Lna_norescale
	s_and_saveexec_b64 vcc, s[4:5]
	ds_write_b32 v170, v243 offset:32768
	s_or_b64 exec, exec, vcc
	s_waitcnt lgkmcnt(0)
	v_add_u32_e32 v0, s82, v108
	ds_read_b128 v[220:223], v0 offset:32864
	ds_read_b128 v[224:227], v0 offset:32832
	ds_read_b128 v[228:231], v0 offset:32800
	ds_read_b128 v[232:235], v0 offset:32768
	s_waitcnt lgkmcnt(0)
	v_pk_mul_f32 v[28:29], v[28:29], v[220:221]
	v_pk_mul_f32 v[30:31], v[30:31], v[222:223]
	v_pk_mul_f32 v[24:25], v[24:25], v[224:225]
	v_pk_mul_f32 v[26:27], v[26:27], v[226:227]
	v_pk_mul_f32 v[20:21], v[20:21], v[228:229]
	v_pk_mul_f32 v[22:23], v[22:23], v[230:231]
	v_pk_mul_f32 v[16:17], v[16:17], v[232:233]
	v_pk_mul_f32 v[18:19], v[18:19], v[234:235]
	v_pk_mul_f32 v[44:45], v[44:45], v[220:221]
	v_pk_mul_f32 v[46:47], v[46:47], v[222:223]
	v_pk_mul_f32 v[40:41], v[40:41], v[224:225]
	v_pk_mul_f32 v[42:43], v[42:43], v[226:227]
	v_pk_mul_f32 v[36:37], v[36:37], v[228:229]
	v_pk_mul_f32 v[38:39], v[38:39], v[230:231]
	v_pk_mul_f32 v[32:33], v[32:33], v[232:233]
	v_pk_mul_f32 v[34:35], v[34:35], v[234:235]
; __device__ __forceinline__ void partialSM(f32x16& p0, f32x16& p1, float& m_reg, float& mn, float& alpha) {
;     ...
;   float mnC = -mn * C;
; #pragma unroll
;   for (int r = 0; r < 16; ++r) p0[r] = fmaf(p0[r], C, mnC);
; #pragma unroll
;   for (int r = 0; r < 16; ++r) p1[r] = fmaf(p1[r], C, mnC);
; #pragma unroll
;   for (int r = 0; r < 16; ++r) p0[r] = __builtin_amdgcn_exp2f(p0[r]);
; }
; __device__ __forceinline__ void finishSM(f32x16& p0, f32x16& p1, float alpha, float& l_reg, bf16x8& pa0, bf16x8& pa1, bf16x8& pa2, bf16x8& pa3) {
; #pragma unroll
;   for (int r = 0; r < 16; ++r) p1[r] = __builtin_amdgcn_exp2f(p1[r]);
;   float ps = 0;
; #pragma unroll
;   for (int r = 0; r < 16; ++r) ps += p0[r];
; #pragma unroll
;   for (int r = 0; r < 16; ++r) ps += p1[r];
;   { auto rr = __builtin_amdgcn_permlane32_swap(__float_as_uint(ps), __float_as_uint(ps), false, false);
;     ps = __uint_as_float(rr[0]) + __uint_as_float(rr[1]); }
;   l_reg = l_reg * alpha + ps;
;     ...
;   PK4(p0, 0, pa0); PK4(p0, 8, pa1); PK4(p1, 0, pa2); PK4(p1, 8, pa3);
; __device__ __forceinline__ void na_items(const Params& p, int l, int L, char* shm, const int tid, const int local, const int G, const int nNA) {
;     ...
;         PVSTEP(pa0, 0); PVSTEP(pa1, 1); PVSTEP(pa2, 2); PVSTEP(pa3, 3);
.Lna_norescale:
	v_cndmask_b32_e64 v210, v238, v210, s[42:43]
	v_mul_f32_e32 v246, 0xbe38aa3b, v210
	ds_read_b128 v[220:223], v240 offset:16384
	ds_read_b128 v[224:227], v240 offset:20480
	ds_read_b128 v[228:231], v241 offset:16384
	ds_read_b128 v[232:235], v241 offset:20480
	v_fmamk_f32 v64, v64, 0x3e38aa3b, v246
	v_fmamk_f32 v65, v65, 0x3e38aa3b, v246
	v_fmamk_f32 v66, v66, 0x3e38aa3b, v246
	v_fmamk_f32 v67, v67, 0x3e38aa3b, v246
	v_fmamk_f32 v68, v68, 0x3e38aa3b, v246
	v_fmamk_f32 v69, v69, 0x3e38aa3b, v246
	v_fmamk_f32 v70, v70, 0x3e38aa3b, v246
	v_fmamk_f32 v71, v71, 0x3e38aa3b, v246
	v_fmamk_f32 v72, v72, 0x3e38aa3b, v246
	v_fmamk_f32 v73, v73, 0x3e38aa3b, v246
	v_fmamk_f32 v74, v74, 0x3e38aa3b, v246
	v_fmamk_f32 v75, v75, 0x3e38aa3b, v246
	v_fmamk_f32 v76, v76, 0x3e38aa3b, v246
	v_fmamk_f32 v77, v77, 0x3e38aa3b, v246
	v_fmamk_f32 v78, v78, 0x3e38aa3b, v246
	v_fmamk_f32 v79, v79, 0x3e38aa3b, v246
	v_exp_f32_e32 v64, v64
	v_exp_f32_e32 v65, v65
	v_exp_f32_e32 v66, v66
	v_exp_f32_e32 v67, v67
	v_exp_f32_e32 v68, v68
	v_exp_f32_e32 v69, v69
	v_exp_f32_e32 v70, v70
	v_exp_f32_e32 v71, v71
	v_exp_f32_e32 v72, v72
	v_exp_f32_e32 v73, v73
	v_exp_f32_e32 v74, v74
	v_exp_f32_e32 v75, v75
	v_exp_f32_e32 v76, v76
	v_exp_f32_e32 v77, v77
	v_exp_f32_e32 v78, v78
	v_exp_f32_e32 v79, v79
	v_cvt_pk_bf16_f32 v212, v64, v65
	v_cvt_pk_bf16_f32 v213, v66, v67
	v_cvt_pk_bf16_f32 v214, v68, v69
	v_cvt_pk_bf16_f32 v215, v70, v71
	v_cvt_pk_bf16_f32 v216, v72, v73
	v_cvt_pk_bf16_f32 v217, v74, v75
	v_cvt_pk_bf16_f32 v218, v76, v77
	v_cvt_pk_bf16_f32 v219, v78, v79
	v_permlane32_swap_b32_e32 v212, v214
	v_permlane32_swap_b32_e32 v213, v215
	v_permlane32_swap_b32_e32 v216, v218
	v_permlane32_swap_b32_e32 v217, v219
	v_add_f32_e32 v249, v65, v64
	v_add_f32_e32 v249, v66, v249
	v_add_f32_e32 v249, v67, v249
	v_add_f32_e32 v249, v68, v249
	v_add_f32_e32 v249, v69, v249
	v_add_f32_e32 v249, v70, v249
	v_add_f32_e32 v249, v71, v249
	v_add_f32_e32 v249, v72, v249
	v_add_f32_e32 v249, v73, v249
	v_add_f32_e32 v249, v74, v249
	v_add_f32_e32 v249, v75, v249
	v_add_f32_e32 v249, v76, v249
	v_add_f32_e32 v249, v77, v249
	v_add_f32_e32 v249, v78, v249
	v_add_f32_e32 v249, v79, v249
	s_waitcnt lgkmcnt(4)
	v_mfma_f32_32x32x16_bf16 v[16:31], v[212:215], v[2:5], v[16:31]
	v_fmamk_f32 v48, v48, 0x3e38aa3b, v246
	v_fmamk_f32 v49, v49, 0x3e38aa3b, v246
	v_fmamk_f32 v50, v50, 0x3e38aa3b, v246
	v_fmamk_f32 v51, v51, 0x3e38aa3b, v246
	v_fmamk_f32 v52, v52, 0x3e38aa3b, v246
	v_fmamk_f32 v53, v53, 0x3e38aa3b, v246
	v_fmamk_f32 v54, v54, 0x3e38aa3b, v246
	v_fmamk_f32 v55, v55, 0x3e38aa3b, v246
	v_mfma_f32_32x32x16_bf16 v[32:47], v[212:215], v[6:9], v[32:47]
	v_fmamk_f32 v56, v56, 0x3e38aa3b, v246
	v_fmamk_f32 v57, v57, 0x3e38aa3b, v246
	v_fmamk_f32 v58, v58, 0x3e38aa3b, v246
	v_fmamk_f32 v59, v59, 0x3e38aa3b, v246
	v_fmamk_f32 v60, v60, 0x3e38aa3b, v246
	v_fmamk_f32 v61, v61, 0x3e38aa3b, v246
	v_fmamk_f32 v62, v62, 0x3e38aa3b, v246
	v_fmamk_f32 v63, v63, 0x3e38aa3b, v246
	v_mfma_f32_32x32x16_bf16 v[16:31], v[216:219], v[10:13], v[16:31]
	v_exp_f32_e32 v48, v48
	v_exp_f32_e32 v49, v49
	v_exp_f32_e32 v50, v50
	v_exp_f32_e32 v51, v51
	v_exp_f32_e32 v52, v52
	v_exp_f32_e32 v53, v53
	v_exp_f32_e32 v54, v54
	v_exp_f32_e32 v55, v55
	v_mfma_f32_32x32x16_bf16 v[32:47], v[216:219], v[250:253], v[32:47]
	v_exp_f32_e32 v56, v56
	v_exp_f32_e32 v57, v57
	v_exp_f32_e32 v58, v58
	v_exp_f32_e32 v59, v59
	v_exp_f32_e32 v60, v60
	v_exp_f32_e32 v61, v61
	v_exp_f32_e32 v62, v62
	v_exp_f32_e32 v63, v63
	v_cvt_pk_bf16_f32 v72, v48, v49
	v_cvt_pk_bf16_f32 v73, v50, v51
	v_cvt_pk_bf16_f32 v74, v52, v53
	v_cvt_pk_bf16_f32 v75, v54, v55
	v_cvt_pk_bf16_f32 v76, v56, v57
	v_cvt_pk_bf16_f32 v77, v58, v59
	v_cvt_pk_bf16_f32 v78, v60, v61
	v_cvt_pk_bf16_f32 v79, v62, v63
	v_permlane32_swap_b32_e32 v72, v74
	v_permlane32_swap_b32_e32 v73, v75
	v_permlane32_swap_b32_e32 v76, v78
	v_permlane32_swap_b32_e32 v77, v79
	s_waitcnt lgkmcnt(0)
	v_mfma_f32_32x32x16_bf16 v[16:31], v[72:75], v[220:223], v[16:31]
	v_add_f32_e32 v249, v48, v249
	v_add_f32_e32 v249, v49, v249
	v_add_f32_e32 v249, v50, v249
	v_add_f32_e32 v249, v51, v249
	v_add_f32_e32 v249, v52, v249
	v_mfma_f32_32x32x16_bf16 v[32:47], v[72:75], v[224:227], v[32:47]
	v_add_f32_e32 v249, v53, v249
	v_add_f32_e32 v249, v54, v249
	v_add_f32_e32 v249, v55, v249
	v_add_f32_e32 v249, v56, v249
	v_add_f32_e32 v249, v57, v249
	v_mfma_f32_32x32x16_bf16 v[16:31], v[76:79], v[228:231], v[16:31]
	v_add_f32_e32 v249, v58, v249
	v_add_f32_e32 v249, v59, v249
	v_add_f32_e32 v249, v60, v249
	v_add_f32_e32 v249, v61, v249
	v_add_f32_e32 v249, v62, v249
	v_add_f32_e32 v249, v63, v249
	v_mfma_f32_32x32x16_bf16 v[32:47], v[76:79], v[232:235], v[32:47]
	v_mov_b32_e32 v238, v249
	s_nop 1
	v_permlane32_swap_b32_e32 v249, v238
	v_add_f32_e32 v0, v249, v238
	v_fmac_f32_e32 v0, v209, v243
	v_mov_b32_e32 v209, v0

; #define SCHED() __builtin_amdgcn_sched_barrier(0)
; #define GLOADS(KS, VS, t, slot) do { char* lb_ = shm + (slot) * 16384 + wid * 1024;                                  \
;     __builtin_amdgcn_global_load_lds((const unsigned*)((KS) + (size_t)(t) * 64 * PW), (unsigned*)(lb_), 16, 0, 0);    \
;     __builtin_amdgcn_global_load_lds((const unsigned*)((VS) + (t) * 64), (unsigned*)(lb_ + 8192), 16, 0, 0); } while (0)
; #define PART(P0, P1) do { _Pragma("unroll") for (int r = 0; r < 16; ++r) FMK(P0[r]);                             \
;     _Pragma("unroll") for (int r = 0; r < 16; ++r) FMK(P1[r]);                                                    \
;     _Pragma("unroll") for (int r = 0; r < 16; ++r) P0[r] = __builtin_amdgcn_exp2f(P0[r]); } while (0)
; #define EXP1(P1) do { _Pragma("unroll") for (int r = 0; r < 16; ++r) P1[r] = __builtin_amdgcn_exp2f(P1[r]); } while (0)
; #define PACK(P0, P1) do { float ps_ = 0.f; _Pragma("unroll") for (int r = 0; r < 16; ++r) ps_ += P0[r] + P1[r]; lsum += ps_;  \
;     PK4(P0, 0, pa0); PK4(P0, 8, pa1); PK4(P1, 0, pa2); PK4(P1, 8, pa3); } while (0)
; #define KFR(slot) do { const char* Kc = shm + (slot) * 16384;                                                      \
;     _Pragma("unroll") for (int d0 = 0; d0 < 4; ++d0) { fr_[d0 * 2] = *(const bf16x8*)(Kc + roff[d0]); fr_[d0 * 2 + 1] = *(const bf16x8*)(Kc + roff[d0] + 4096); } } while (0)
; #define PVM() do { PV1(pa0, 0); PV1(pa1, 1); PV1(pa2, 2); PV1(pa3, 3); } while (0)
; __device__ __forceinline__ void gqa_items(const Params& p, int l, int L, char* shm, const int tid, const int local, const int G, const int nGQ) {
;     ...
;     for (int j = 0; j < NT; ++j) {
;       if (j + 2 < NT) { const int ns_ = (cur == 0) ? 2 : cur - 1; GLOADS(Ks, Vs, j + 2, ns_); }
;       SCHED(); KFR(cur); SCHED();
;       QKT(pA0, pA1); SCHED();
;       PART(pA0, pA1); EXP1(pA1); SCHED();
;       VFR(cur); SCHED();
;       PACK(pA0, pA1); SCHED();
;       PVM();
;       SCHED();
;       if (j + 2 < NT) asm volatile("s_waitcnt vmcnt(2) lgkmcnt(0)" ::: "memory"); else asm volatile("s_waitcnt vmcnt(0) lgkmcnt(0)" ::: "memory");
;       __builtin_amdgcn_s_barrier(); asm volatile("" ::: "memory"); SCHED();
;       cur = (cur == 2) ? 0 : cur + 1;
;     }
.LBB0_536:
	s_lshl_b32 s16, s14, 14
	s_add_i32 s2, s15, 2
	s_cmp_ge_u32 s2, s96
	v_add_u32_e32 v224, s16, v109
	v_add_u32_e32 v225, s16, v120
	v_add_u32_e32 v226, s16, v121
	v_add_u32_e32 v227, s16, v122
	ds_read_b128 v[192:195], v224
	ds_read_b128 v[196:199], v224 offset:4096
	ds_read_b128 v[200:203], v225
	ds_read_b128 v[204:207], v225 offset:4096
	ds_read_b128 v[208:211], v226
	ds_read_b128 v[212:215], v226 offset:4096
	ds_read_b128 v[216:219], v227
	ds_read_b128 v[220:223], v227 offset:4096
	s_cbranch_scc1 .Lgq_nold
	s_add_i32 s2, s16, 0xffffc000
	s_cmp_lg_u32 s14, 0
	s_cselect_b32 s2, s2, 0x8000
	s_add_i32 s2, s7, s2
	s_mov_b32 m0, s2
	v_lshl_add_u64 v[228:229], s[58:59], 1, v[74:75]
	global_load_lds_dwordx4 v[78:79], off
	s_add_i32 m0, s2, 0x2000
	s_nop 0
	global_load_lds_dwordx4 v[228:229], off
.Lgq_nold:
	s_waitcnt lgkmcnt(7)
	v_mfma_f32_32x32x16_bf16 v[34:49], v[192:195], v[50:53], 0
	ds_read_b128 v[144:147], v224 offset:8192
	s_waitcnt lgkmcnt(7)
	v_mfma_f32_32x32x16_bf16 v[128:143], v[196:199], v[50:53], 0
	ds_read_b128 v[148:151], v224 offset:12288
	s_waitcnt lgkmcnt(7)
	v_mfma_f32_32x32x16_bf16 v[34:49], v[200:203], v[54:57], v[34:49]
	ds_read_b128 v[152:155], v225 offset:8192
	s_waitcnt lgkmcnt(7)
	v_mfma_f32_32x32x16_bf16 v[128:143], v[204:207], v[54:57], v[128:143]
	ds_read_b128 v[156:159], v225 offset:12288
	s_waitcnt lgkmcnt(7)
	v_mfma_f32_32x32x16_bf16 v[34:49], v[208:211], v[58:61], v[34:49]
	ds_read_b128 v[160:163], v226 offset:8192
	s_waitcnt lgkmcnt(7)
	v_mfma_f32_32x32x16_bf16 v[128:143], v[212:215], v[58:61], v[128:143]
	ds_read_b128 v[164:167], v226 offset:12288
	s_waitcnt lgkmcnt(7)
	v_mfma_f32_32x32x16_bf16 v[34:49], v[216:219], v[62:65], v[34:49]
	ds_read_b128 v[168:171], v227 offset:8192
	s_waitcnt lgkmcnt(7)
	v_mfma_f32_32x32x16_bf16 v[128:143], v[220:223], v[62:65], v[128:143]
	ds_read_b128 v[172:175], v227 offset:12288
	s_nop 9
	v_fmamk_f32 v34, v34, 0x3e38aa3b, v71
	v_fmamk_f32 v35, v35, 0x3e38aa3b, v71
	v_fmamk_f32 v36, v36, 0x3e38aa3b, v71
	v_fmamk_f32 v37, v37, 0x3e38aa3b, v71
	v_fmamk_f32 v38, v38, 0x3e38aa3b, v71
	v_fmamk_f32 v39, v39, 0x3e38aa3b, v71
	v_fmamk_f32 v40, v40, 0x3e38aa3b, v71
	v_fmamk_f32 v41, v41, 0x3e38aa3b, v71
	v_fmamk_f32 v42, v42, 0x3e38aa3b, v71
	v_fmamk_f32 v43, v43, 0x3e38aa3b, v71
	v_fmamk_f32 v44, v44, 0x3e38aa3b, v71
	v_fmamk_f32 v45, v45, 0x3e38aa3b, v71
	v_fmamk_f32 v46, v46, 0x3e38aa3b, v71
	v_fmamk_f32 v47, v47, 0x3e38aa3b, v71
	v_fmamk_f32 v48, v48, 0x3e38aa3b, v71
	v_fmamk_f32 v49, v49, 0x3e38aa3b, v71
	v_exp_f32_e32 v34, v34
	v_exp_f32_e32 v35, v35
	v_exp_f32_e32 v36, v36
	v_exp_f32_e32 v37, v37
	v_exp_f32_e32 v38, v38
	v_exp_f32_e32 v39, v39
	v_exp_f32_e32 v40, v40
	v_exp_f32_e32 v41, v41
	v_exp_f32_e32 v42, v42
	v_exp_f32_e32 v43, v43
	v_exp_f32_e32 v44, v44
	v_exp_f32_e32 v45, v45
	v_exp_f32_e32 v46, v46
	v_exp_f32_e32 v47, v47
	v_exp_f32_e32 v48, v48
	v_exp_f32_e32 v49, v49
	v_cvt_pk_bf16_f32 v176, v34, v35
	v_cvt_pk_bf16_f32 v177, v36, v37
	v_cvt_pk_bf16_f32 v178, v38, v39
	v_cvt_pk_bf16_f32 v179, v40, v41
	v_cvt_pk_bf16_f32 v180, v42, v43
	v_cvt_pk_bf16_f32 v181, v44, v45
	v_cvt_pk_bf16_f32 v182, v46, v47
	v_cvt_pk_bf16_f32 v183, v48, v49
	v_permlane32_swap_b32_e32 v176, v178
	v_permlane32_swap_b32_e32 v177, v179
	v_permlane32_swap_b32_e32 v180, v182
	v_permlane32_swap_b32_e32 v181, v183
	s_waitcnt lgkmcnt(0)
	v_mfma_f32_32x32x16_bf16 v[18:33], v[176:179], v[144:147], v[18:33]
	v_fmamk_f32 v128, v128, 0x3e38aa3b, v71
	v_fmamk_f32 v129, v129, 0x3e38aa3b, v71
	v_fmamk_f32 v130, v130, 0x3e38aa3b, v71
	v_fmamk_f32 v131, v131, 0x3e38aa3b, v71
	v_fmamk_f32 v132, v132, 0x3e38aa3b, v71
	v_fmamk_f32 v133, v133, 0x3e38aa3b, v71
	v_fmamk_f32 v134, v134, 0x3e38aa3b, v71
	v_fmamk_f32 v135, v135, 0x3e38aa3b, v71
	v_mfma_f32_32x32x16_bf16 v[2:17], v[176:179], v[148:151], v[2:17]
	v_fmamk_f32 v136, v136, 0x3e38aa3b, v71
	v_fmamk_f32 v137, v137, 0x3e38aa3b, v71
	v_fmamk_f32 v138, v138, 0x3e38aa3b, v71
	v_fmamk_f32 v139, v139, 0x3e38aa3b, v71
	v_fmamk_f32 v140, v140, 0x3e38aa3b, v71
	v_fmamk_f32 v141, v141, 0x3e38aa3b, v71
	v_fmamk_f32 v142, v142, 0x3e38aa3b, v71
	v_fmamk_f32 v143, v143, 0x3e38aa3b, v71
	v_mfma_f32_32x32x16_bf16 v[18:33], v[180:183], v[152:155], v[18:33]
	v_exp_f32_e32 v128, v128
	v_exp_f32_e32 v129, v129
	v_exp_f32_e32 v130, v130
	v_exp_f32_e32 v131, v131
	v_exp_f32_e32 v132, v132
	v_exp_f32_e32 v133, v133
	v_exp_f32_e32 v134, v134
	v_exp_f32_e32 v135, v135
	v_mfma_f32_32x32x16_bf16 v[2:17], v[180:183], v[156:159], v[2:17]
	v_exp_f32_e32 v136, v136
	v_exp_f32_e32 v137, v137
	v_exp_f32_e32 v138, v138
	v_exp_f32_e32 v139, v139
	v_exp_f32_e32 v140, v140
	v_exp_f32_e32 v141, v141
	v_exp_f32_e32 v142, v142
	v_exp_f32_e32 v143, v143
	v_cvt_pk_bf16_f32 v184, v128, v129
	v_cvt_pk_bf16_f32 v185, v130, v131
	v_cvt_pk_bf16_f32 v186, v132, v133
	v_cvt_pk_bf16_f32 v187, v134, v135
	v_cvt_pk_bf16_f32 v188, v136, v137
	v_cvt_pk_bf16_f32 v189, v138, v139
	v_cvt_pk_bf16_f32 v190, v140, v141
	v_cvt_pk_bf16_f32 v191, v142, v143
	v_permlane32_swap_b32_e32 v184, v186
	v_permlane32_swap_b32_e32 v185, v187
	v_permlane32_swap_b32_e32 v188, v190
	v_permlane32_swap_b32_e32 v189, v191
	v_add_f32_e32 v34, v34, v128
	v_add_f32_e32 v35, v35, v129
	v_mfma_f32_32x32x16_bf16 v[18:33], v[184:187], v[160:163], v[18:33]
	v_add_f32_e32 v36, v36, v130
	v_add_f32_e32 v37, v37, v131
	v_add_f32_e32 v38, v38, v132
	v_add_f32_e32 v39, v39, v133
	v_add_f32_e32 v40, v40, v134
	v_add_f32_e32 v41, v41, v135
	v_add_f32_e32 v42, v42, v136
	v_add_f32_e32 v43, v43, v137
	v_mfma_f32_32x32x16_bf16 v[2:17], v[184:187], v[164:167], v[2:17]
	v_add_f32_e32 v44, v44, v138
	v_add_f32_e32 v45, v45, v139
	v_add_f32_e32 v46, v46, v140
	v_add_f32_e32 v47, v47, v141
	v_add_f32_e32 v48, v48, v142
	v_add_f32_e32 v49, v49, v143
	v_add_f32_e32 v35, v35, v34
	v_add_f32_e32 v36, v36, v35
	v_mfma_f32_32x32x16_bf16 v[18:33], v[188:191], v[168:171], v[18:33]
	v_add_f32_e32 v37, v37, v36
	v_add_f32_e32 v38, v38, v37
	v_add_f32_e32 v39, v39, v38
	v_add_f32_e32 v40, v40, v39
	v_add_f32_e32 v41, v41, v40
	v_add_f32_e32 v42, v42, v41
	v_add_f32_e32 v43, v43, v42
	v_add_f32_e32 v44, v44, v43
	v_mfma_f32_32x32x16_bf16 v[2:17], v[188:191], v[172:175], v[2:17]
	v_add_f32_e32 v45, v45, v44
	v_add_f32_e32 v46, v46, v45
	v_add_f32_e32 v47, v47, v46
	v_add_f32_e32 v48, v48, v47
	v_add_f32_e32 v49, v49, v48
	v_add_f32_e32 v127, v127, v49
	s_add_i32 s2, s15, 2
	s_cmp_ge_u32 s2, s96
	s_cbranch_scc1 .Lgq_w0
	s_waitcnt vmcnt(2) lgkmcnt(0)
	s_branch .Lgq_w1
.Lgq_w0:
	s_waitcnt vmcnt(0) lgkmcnt(0)
.Lgq_w1:
	s_barrier
	s_add_i32 s0, s14, 1
	s_cmp_lg_u32 s14, 2
	s_cselect_b32 s14, s0, 0
	s_add_i32 s15, s15, 1
	s_add_i32 s58, s58, 64
	s_cmp_eq_u32 s96, s15
	v_lshl_add_u64 v[78:79], v[78:79], 0, s[92:93]
	s_cbranch_scc0 .LBB0_536

; #define KLOOP(K0, K1) _Pragma("unroll 1") for (int kt = (K0); kt < (K1); ++kt) { const int cur = kt & 1;        \
;       if (kt + 1 < 16) GLDS_STAGE(cur ^ 1, kt + 1);                                                               \
;       const char* ab = a0 + cur * STAGE_B; const char* bb = b0 + cur * STAGE_B;                                  \
;       COMPUTE(ab, bb); WAIT_V(0); __syncthreads(); }
; template <int MODE>
; __device__ __forceinline__ void gemm_phase(const Params& p, int l, int cb, char* shm) {
;     ...
;     if (MODE == 2) {
;       KLOOP(0, 8);
.LBB0_590:
	s_and_b32 s31, s7, 0x10000
	s_xor_b32 s33, s31, 0x10000
	s_add_i32 s33, s20, s33
	s_add_i32 s34, s33, 0x8000
	v_or_b32_e32 v179, s31, v237
	v_add_u32_e32 v178, s31, v253
	v_add_u32_e32 v230, v178, v252
	ds_read_b128 v[146:149], v179 offset:32768
	ds_read_b128 v[150:153], v179 offset:34816
	ds_read_b128 v[154:157], v179 offset:36864
	ds_read_b128 v[158:161], v179 offset:38912
	ds_read_b128 v[162:165], v178
	ds_read_b128 v[166:169], v178 offset:2048
	ds_read_b128 v[170:173], v178 offset:4096
	ds_read_b128 v[174:177], v178 offset:6144
	v_lshl_add_u64 v[186:187], v[130:131], 0, s[0:1]
	s_mov_b32 m0, s33
	s_nop 0
	global_load_lds_dwordx4 v[186:187], off
	v_lshl_add_u64 v[186:187], v[138:139], 0, s[0:1]
	s_mov_b32 m0, s34
	s_nop 0
	global_load_lds_dwordx4 v[186:187], off
	s_waitcnt lgkmcnt(0)
	v_mfma_f32_16x16x32_bf16 v[2:5], v[146:149], v[162:165], v[2:5]
	v_mfma_f32_16x16x32_bf16 v[6:9], v[150:153], v[162:165], v[6:9]
	v_lshl_add_u64 v[186:187], v[132:133], 0, s[0:1]
	s_add_i32 m0, s33, 0x2000
	s_nop 0
	global_load_lds_dwordx4 v[186:187], off
	v_mfma_f32_16x16x32_bf16 v[10:13], v[154:157], v[162:165], v[10:13]
	v_mfma_f32_16x16x32_bf16 v[14:17], v[158:161], v[162:165], v[14:17]
	v_mfma_f32_16x16x32_bf16 v[18:21], v[146:149], v[166:169], v[18:21]
	v_mfma_f32_16x16x32_bf16 v[26:29], v[150:153], v[166:169], v[26:29]
	v_lshl_add_u64 v[186:187], v[140:141], 0, s[0:1]
	s_add_i32 m0, s33, 0xa000
	s_nop 0
	global_load_lds_dwordx4 v[186:187], off
	v_mfma_f32_16x16x32_bf16 v[34:37], v[154:157], v[166:169], v[34:37]
	v_mfma_f32_16x16x32_bf16 v[42:45], v[158:161], v[166:169], v[42:45]
	ds_read_b128 v[162:165], v178 offset:8192
	ds_read_b128 v[166:169], v178 offset:10240
	v_mfma_f32_16x16x32_bf16 v[54:57], v[146:149], v[170:173], v[54:57]
	v_mfma_f32_16x16x32_bf16 v[62:65], v[150:153], v[170:173], v[62:65]
	v_lshl_add_u64 v[186:187], v[134:135], 0, s[0:1]
	s_add_i32 m0, s33, 0x4000
	s_nop 0
	global_load_lds_dwordx4 v[186:187], off
	v_mfma_f32_16x16x32_bf16 v[70:73], v[154:157], v[170:173], v[70:73]
	v_mfma_f32_16x16x32_bf16 v[74:77], v[158:161], v[170:173], v[74:77]
	v_mfma_f32_16x16x32_bf16 v[82:85], v[146:149], v[174:177], v[82:85]
	v_mfma_f32_16x16x32_bf16 v[90:93], v[150:153], v[174:177], v[90:93]
	v_lshl_add_u64 v[186:187], v[142:143], 0, s[0:1]
	s_add_i32 m0, s33, 0xc000
	s_nop 0
	global_load_lds_dwordx4 v[186:187], off
	v_mfma_f32_16x16x32_bf16 v[102:105], v[154:157], v[174:177], v[102:105]
	v_mfma_f32_16x16x32_bf16 v[114:117], v[158:161], v[174:177], v[114:117]
	ds_read_b128 v[170:173], v178 offset:12288
	ds_read_b128 v[174:177], v178 offset:14336
	s_waitcnt lgkmcnt(0)
	v_mfma_f32_16x16x32_bf16 v[86:89], v[146:149], v[162:165], v[86:89]
	v_add_u32_e32 v182, v179, v252
	v_mfma_f32_16x16x32_bf16 v[94:97], v[150:153], v[162:165], v[94:97]
	v_lshl_add_u64 v[186:187], v[136:137], 0, s[0:1]
	s_add_i32 m0, s33, 0x6000
	s_nop 0
	global_load_lds_dwordx4 v[186:187], off
	v_mfma_f32_16x16x32_bf16 v[106:109], v[154:157], v[162:165], v[106:109]
	v_mfma_f32_16x16x32_bf16 v[118:121], v[158:161], v[162:165], v[118:121]
	v_mfma_f32_16x16x32_bf16 v[126:129], v[146:149], v[166:169], v[126:129]
	v_mfma_f32_16x16x32_bf16 v[122:125], v[150:153], v[166:169], v[122:125]
	v_lshl_add_u64 v[186:187], v[144:145], 0, s[0:1]
	s_add_i32 m0, s33, 0xe000
	s_nop 0
	global_load_lds_dwordx4 v[186:187], off
	v_mfma_f32_16x16x32_bf16 v[110:113], v[154:157], v[166:169], v[110:113]
	v_mfma_f32_16x16x32_bf16 v[98:101], v[158:161], v[166:169], v[98:101]
	ds_read_b128 v[162:165], v182 offset:32768
	ds_read_b128 v[166:169], v182 offset:34816
	ds_read_b128 v[178:181], v182 offset:36864
	ds_read_b128 v[182:185], v182 offset:38912
	ds_read_b128 v[186:189], v230
	ds_read_b128 v[198:201], v230 offset:2048
	v_mfma_f32_16x16x32_bf16 v[78:81], v[146:149], v[170:173], v[78:81]
	v_mfma_f32_16x16x32_bf16 v[66:69], v[150:153], v[170:173], v[66:69]
	v_mfma_f32_16x16x32_bf16 v[58:61], v[154:157], v[170:173], v[58:61]
	v_mfma_f32_16x16x32_bf16 v[50:53], v[158:161], v[170:173], v[50:53]
	v_mfma_f32_16x16x32_bf16 v[46:49], v[146:149], v[174:177], v[46:49]
	v_mfma_f32_16x16x32_bf16 v[38:41], v[150:153], v[174:177], v[38:41]
	v_mfma_f32_16x16x32_bf16 v[30:33], v[154:157], v[174:177], v[30:33]
	v_mfma_f32_16x16x32_bf16 v[22:25], v[158:161], v[174:177], v[22:25]
	ds_read_b128 v[146:149], v230 offset:4096
	ds_read_b128 v[150:153], v230 offset:6144
	s_waitcnt lgkmcnt(0)
	v_mfma_f32_16x16x32_bf16 v[2:5], v[162:165], v[186:189], v[2:5]
	v_mfma_f32_16x16x32_bf16 v[6:9], v[166:169], v[186:189], v[6:9]
	v_mfma_f32_16x16x32_bf16 v[10:13], v[178:181], v[186:189], v[10:13]
	v_mfma_f32_16x16x32_bf16 v[14:17], v[182:185], v[186:189], v[14:17]
	v_mfma_f32_16x16x32_bf16 v[18:21], v[162:165], v[198:201], v[18:21]
	v_mfma_f32_16x16x32_bf16 v[26:29], v[166:169], v[198:201], v[26:29]
	v_mfma_f32_16x16x32_bf16 v[34:37], v[178:181], v[198:201], v[34:37]
	v_mfma_f32_16x16x32_bf16 v[42:45], v[182:185], v[198:201], v[42:45]
	ds_read_b128 v[154:157], v230 offset:8192
	ds_read_b128 v[158:161], v230 offset:10240
	v_mfma_f32_16x16x32_bf16 v[54:57], v[162:165], v[146:149], v[54:57]
	v_mfma_f32_16x16x32_bf16 v[62:65], v[166:169], v[146:149], v[62:65]
	v_mfma_f32_16x16x32_bf16 v[70:73], v[178:181], v[146:149], v[70:73]
	v_mfma_f32_16x16x32_bf16 v[74:77], v[182:185], v[146:149], v[74:77]
	v_mfma_f32_16x16x32_bf16 v[82:85], v[162:165], v[150:153], v[82:85]
	v_mfma_f32_16x16x32_bf16 v[90:93], v[166:169], v[150:153], v[90:93]
	v_mfma_f32_16x16x32_bf16 v[102:105], v[178:181], v[150:153], v[102:105]
	v_mfma_f32_16x16x32_bf16 v[114:117], v[182:185], v[150:153], v[114:117]
	ds_read_b128 v[146:149], v230 offset:12288
	ds_read_b128 v[150:153], v230 offset:14336
	s_waitcnt lgkmcnt(0)
	v_mfma_f32_16x16x32_bf16 v[86:89], v[162:165], v[154:157], v[86:89]
	v_mfma_f32_16x16x32_bf16 v[94:97], v[166:169], v[154:157], v[94:97]
	v_mfma_f32_16x16x32_bf16 v[106:109], v[178:181], v[154:157], v[106:109]
	v_mfma_f32_16x16x32_bf16 v[118:121], v[182:185], v[154:157], v[118:121]
	v_mfma_f32_16x16x32_bf16 v[126:129], v[162:165], v[158:161], v[126:129]
	v_mfma_f32_16x16x32_bf16 v[122:125], v[166:169], v[158:161], v[122:125]
	v_mfma_f32_16x16x32_bf16 v[110:113], v[178:181], v[158:161], v[110:113]
	v_mfma_f32_16x16x32_bf16 v[98:101], v[182:185], v[158:161], v[98:101]
	v_mfma_f32_16x16x32_bf16 v[78:81], v[162:165], v[146:149], v[78:81]
	v_mfma_f32_16x16x32_bf16 v[66:69], v[166:169], v[146:149], v[66:69]
	v_mfma_f32_16x16x32_bf16 v[58:61], v[178:181], v[146:149], v[58:61]
	v_mfma_f32_16x16x32_bf16 v[50:53], v[182:185], v[146:149], v[50:53]
	v_mfma_f32_16x16x32_bf16 v[46:49], v[162:165], v[150:153], v[46:49]
	v_mfma_f32_16x16x32_bf16 v[38:41], v[166:169], v[150:153], v[38:41]
	v_mfma_f32_16x16x32_bf16 v[30:33], v[178:181], v[150:153], v[30:33]
	v_mfma_f32_16x16x32_bf16 v[22:25], v[182:185], v[150:153], v[22:25]
	s_add_i32 s7, s7, 0x10000
	s_waitcnt vmcnt(0)
	s_add_u32 s0, s0, 0x80
	s_addc_u32 s1, s1, 0
	s_cmpk_eq_i32 s0, 0x400
	s_waitcnt vmcnt(0)
	s_barrier
; __device__ __forceinline__ float bflo(unsigned w) { return __uint_as_float(w << 16); }
; __device__ __forceinline__ float bfhi(unsigned w) { return __uint_as_float(w & 0xffff0000u); }
; #define SCHED() __builtin_amdgcn_sched_barrier(0)
; template <int MODE>
; __device__ __forceinline__ void gemm_phase(const Params& p, int l, int cb, char* shm) {
;     ...
;       {
;         char* est = shm + 65536 + wid * 8192;
;         const int lrow = lane >> 3, lch = lane & 7;
;         const u16* gsrc = p.P + (size_t)(brow + wr * 128 + lrow) * PW + bcol + wc * 64 + lch * 8;
;         u32x4 ra[4], rb[4];
; #pragma unroll
;         for (int i = 0; i < 4; ++i) { ra[i] = *(const u32x4*)(gsrc + (size_t)(8 * i) * PW + PC_GA); rb[i] = *(const u32x4*)(gsrc + (size_t)(8 * i) * PW + PC_GB); }
; #pragma unroll
;         for (int q = 0; q < 4; ++q) {
; #pragma unroll
;           for (int i = 0; i < 4; ++i) {
;             const int so = (lrow + 8 * i) * 128 + ((lch ^ lrow) << 4);
;             *(u32x4*)(est + so) = ra[i]; *(u32x4*)(est + 4096 + so) = rb[i];
;           }
;           SCHED();
;           if (q < 3) {
; #pragma unroll
;             for (int i = 0; i < 4; ++i) { ra[i] = *(const u32x4*)(gsrc + (size_t)(32 * (q + 1) + 8 * i) * PW + PC_GA); rb[i] = *(const u32x4*)(gsrc + (size_t)(32 * (q + 1) + 8 * i) * PW + PC_GB); }
;           }
;           SCHED();
; #pragma unroll
;           for (int mm = 0; mm < 2; ++mm) {
;             const int m = q * 2 + mm, row = mm * 16 + fr;
; #pragma unroll
;             for (int n = 0; n < 4; ++n) {
;               const int off = row * 128 + (((n * 2 + (fq >> 1)) ^ (row & 7)) << 4) + (fq & 1) * 8;
;               const u32x2 ga = *(const u32x2*)(est + off), gb = *(const u32x2*)(est + 4096 + off);
;               acc[m][n][0] *= bflo(ga[0]) * __builtin_amdgcn_rcpf(fmaxf(bflo(gb[0]), 1e-30f));
;               acc[m][n][1] *= bfhi(ga[0]) * __builtin_amdgcn_rcpf(fmaxf(bfhi(gb[0]), 1e-30f));
;               acc[m][n][2] *= bflo(ga[1]) * __builtin_amdgcn_rcpf(fmaxf(bflo(gb[1]), 1e-30f));
;               acc[m][n][3] *= bfhi(ga[1]) * __builtin_amdgcn_rcpf(fmaxf(bfhi(gb[1]), 1e-30f));
;             }
;           }
;           SCHED();
;         }
	s_cbranch_scc0 .LBB0_590
	s_add_i32 s31, s6, s29
	v_add_u32_e32 v230, s31, v249
	v_mov_b64_e32 v[130:131], s[10:11]
	v_mad_i64_i32 v[130:131], s[0:1], v230, s80, v[130:131]
	v_lshl_add_u64 v[130:131], s[12:13], 1, v[130:131]
	v_lshl_add_u64 v[130:131], v[130:131], 0, s[58:59]
	v_lshl_add_u64 v[232:233], v[130:131], 0, v[0:1]
	v_add_co_u32_e32 v134, vcc, 0x1000, v232
	v_mov_b32_e32 v186, v250
	s_nop 0
	v_addc_co_u32_e32 v135, vcc, 0, v233, vcc
	v_add_co_u32_e32 v138, vcc, 0x13000, v232
	v_mov_b32_e32 v162, v251
	s_nop 0
	v_addc_co_u32_e32 v139, vcc, 0, v233, vcc
	v_add_co_u32_e32 v142, vcc, 0x14000, v232
	global_load_dwordx4 v[130:133], v[134:135], off offset:1280
	s_nop 0
	global_load_dwordx4 v[134:137], v[134:135], off offset:3328
	v_addc_co_u32_e32 v143, vcc, 0, v233, vcc
	v_add_co_u32_e32 v150, vcc, 0x26000, v232
	global_load_dwordx4 v[138:141], v[138:139], off offset:3328
	s_nop 0
	global_load_dwordx4 v[142:145], v[142:143], off offset:1280
	v_addc_co_u32_e32 v151, vcc, 0, v233, vcc
	v_add_co_u32_e32 v154, vcc, 0x38000, v232
	global_load_dwordx4 v[146:149], v[150:151], off offset:1280
	s_nop 0
	global_load_dwordx4 v[150:153], v[150:151], off offset:3328
	v_addc_co_u32_e32 v155, vcc, 0, v233, vcc
	v_add_co_u32_e32 v158, vcc, 0x39000, v232
	v_lshlrev_b32_e32 v163, 7, v186
	s_nop 0
	v_addc_co_u32_e32 v159, vcc, 0, v233, vcc
	global_load_dwordx4 v[154:157], v[154:155], off offset:3328
	s_nop 0
	global_load_dwordx4 v[158:161], v[158:159], off offset:1280
	v_lshrrev_b32_e32 v187, 1, v162
	v_lshlrev_b32_e32 v162, 3, v162
	v_and_or_b32 v188, v162, 8, v163
	v_bitop3_b32 v162, v187, v186, 7 bitop3:0x78
	v_ashrrev_i32_e32 v231, 31, v230
	v_lshlrev_b32_e32 v162, 4, v162
	v_add3_u32 v244, v188, v162, s28
	s_waitcnt vmcnt(7)
	ds_write_b128 v238, v[130:133]
	s_waitcnt vmcnt(6)
	ds_write_b128 v238, v[134:137] offset:4096
	s_waitcnt vmcnt(5)
	ds_write_b128 v238, v[138:141] offset:1024
	s_waitcnt vmcnt(4)
	ds_write_b128 v238, v[142:145] offset:5120
	s_waitcnt vmcnt(3)
	ds_write_b128 v238, v[146:149] offset:2048
	s_waitcnt vmcnt(2)
	ds_write_b128 v238, v[150:153] offset:6144
	s_waitcnt vmcnt(1)
	ds_write_b128 v238, v[154:157] offset:3072
	s_waitcnt vmcnt(0)
	ds_write_b128 v238, v[158:161] offset:7168
	s_mov_b32 s0, 0x83000
	v_add_co_u32_e32 v130, vcc, s0, v232
	s_mov_b32 s0, 0x82000
	s_nop 0
	v_addc_co_u32_e32 v131, vcc, 0, v233, vcc
	v_add_co_u32_e32 v134, vcc, s0, v232
	s_mov_b32 s0, 0x70000
	s_nop 0
	v_addc_co_u32_e32 v135, vcc, 0, v233, vcc
	v_add_co_u32_e32 v142, vcc, s0, v232
	s_mov_b32 s0, 0x5e000
	s_nop 0
	v_addc_co_u32_e32 v143, vcc, 0, v233, vcc
	v_add_co_u32_e32 v146, vcc, s0, v232
	s_mov_b32 s0, 0x5d000
	s_nop 0
	v_addc_co_u32_e32 v147, vcc, 0, v233, vcc
	v_add_co_u32_e32 v150, vcc, s0, v232
	s_mov_b32 s0, 0x4b000
	s_nop 0
	v_addc_co_u32_e32 v151, vcc, 0, v233, vcc
	v_add_co_u32_e32 v158, vcc, s0, v232
	global_load_dwordx4 v[130:133], v[130:131], off offset:1280
	s_nop 0
	global_load_dwordx4 v[134:137], v[134:135], off offset:3328
	v_addc_co_u32_e32 v159, vcc, 0, v233, vcc
	global_load_dwordx4 v[138:141], v[142:143], off offset:3328
	s_nop 0
	global_load_dwordx4 v[142:145], v[142:143], off offset:1280
	s_nop 0
	global_load_dwordx4 v[146:149], v[146:147], off offset:1280
	s_nop 0
	global_load_dwordx4 v[150:153], v[150:151], off offset:3328
	s_nop 0
	global_load_dwordx4 v[154:157], v[158:159], off offset:3328
	s_nop 0
	global_load_dwordx4 v[158:161], v[158:159], off offset:1280
	ds_read2st64_b64 v[162:165], v244 offset1:4
	ds_read2st64_b64 v[166:169], v244 offset0:8 offset1:12
	s_waitcnt lgkmcnt(1)
	v_lshlrev_b32_e32 v172, 16, v162
	s_waitcnt lgkmcnt(0)
	v_lshlrev_b32_e32 v170, 16, v166
	v_and_b32_e32 v166, 0xffff0000, v166
	v_and_b32_e32 v173, 0xffff0000, v162
	v_lshlrev_b32_e32 v162, 16, v167
	v_max_f32_e32 v166, v166, v166
	v_max_f32_e32 v162, v162, v162
	v_max_f32_e32 v166, 0xda24260, v166
	v_max_f32_e32 v162, 0xda24260, v162
	v_rcp_f32_e32 v171, v166
	v_rcp_f32_e32 v166, v162
	v_and_b32_e32 v162, 0xffff0000, v167
	v_max_f32_e32 v162, v162, v162
	v_max_f32_e32 v162, 0xda24260, v162
	v_rcp_f32_e32 v167, v162
	v_max_f32_e32 v170, v170, v170
	v_max_f32_e32 v170, 0xda24260, v170
	v_lshlrev_b32_e32 v162, 16, v163
	v_and_b32_e32 v163, 0xffff0000, v163
	v_rcp_f32_e32 v170, v170
	v_pk_mul_f32 v[162:163], v[166:167], v[162:163]
	v_pk_mul_f32 v[170:171], v[170:171], v[172:173]
	v_pk_mul_f32 v[4:5], v[4:5], v[162:163]
	v_add_u32_e32 v162, 2, v187
	v_bitop3_b32 v162, v162, v186, 7 bitop3:0x78
	v_lshlrev_b32_e32 v162, 4, v162
	v_add3_u32 v245, v162, v188, s28
	v_pk_mul_f32 v[2:3], v[2:3], v[170:171]
	ds_read2st64_b64 v[170:173], v245 offset1:4
	ds_read2st64_b64 v[174:177], v245 offset0:8 offset1:12
	s_waitcnt lgkmcnt(1)
	v_lshlrev_b32_e32 v166, 16, v170
	s_waitcnt lgkmcnt(0)
	v_lshlrev_b32_e32 v162, 16, v174
	v_and_b32_e32 v163, 0xffff0000, v174
	v_max_f32_e32 v162, v162, v162
	v_max_f32_e32 v163, v163, v163
	v_max_f32_e32 v162, 0xda24260, v162
	v_max_f32_e32 v163, 0xda24260, v163
	v_rcp_f32_e32 v162, v162
	v_rcp_f32_e32 v163, v163
	v_and_b32_e32 v167, 0xffff0000, v170
	v_pk_mul_f32 v[162:163], v[162:163], v[166:167]
	s_nop 0
	v_pk_mul_f32 v[6:7], v[6:7], v[162:163]
	v_lshlrev_b32_e32 v162, 16, v175
	v_and_b32_e32 v163, 0xffff0000, v175
	v_max_f32_e32 v162, v162, v162
	v_max_f32_e32 v163, v163, v163
	v_max_f32_e32 v162, 0xda24260, v162
	v_max_f32_e32 v163, 0xda24260, v163
	v_rcp_f32_e32 v162, v162
	v_rcp_f32_e32 v163, v163
	v_lshlrev_b32_e32 v166, 16, v171
	v_and_b32_e32 v167, 0xffff0000, v171
	v_pk_mul_f32 v[162:163], v[162:163], v[166:167]
	s_nop 0
	v_pk_mul_f32 v[8:9], v[8:9], v[162:163]
	v_add_u32_e32 v162, 4, v187
	v_bitop3_b32 v162, v162, v186, 7 bitop3:0x78
	v_lshlrev_b32_e32 v162, 4, v162
	v_add3_u32 v246, v162, v188, s28
	ds_read2st64_b64 v[178:181], v246 offset1:4
	ds_read2st64_b64 v[182:185], v246 offset0:8 offset1:12
	s_waitcnt lgkmcnt(1)
; __device__ __forceinline__ float bflo(unsigned w) { return __uint_as_float(w << 16); }
; __device__ __forceinline__ float bfhi(unsigned w) { return __uint_as_float(w & 0xffff0000u); }
; template <int MODE>
; __device__ __forceinline__ void gemm_phase(const Params& p, int l, int cb, char* shm) {
;     ...
; #pragma unroll
;           for (int mm = 0; mm < 2; ++mm) {
;             const int m = q * 2 + mm, row = mm * 16 + fr;
; #pragma unroll
;             for (int n = 0; n < 4; ++n) {
;               const int off = row * 128 + (((n * 2 + (fq >> 1)) ^ (row & 7)) << 4) + (fq & 1) * 8;
;               const u32x2 ga = *(const u32x2*)(est + off), gb = *(const u32x2*)(est + 4096 + off);
;               acc[m][n][0] *= bflo(ga[0]) * __builtin_amdgcn_rcpf(fmaxf(bflo(gb[0]), 1e-30f));
;               acc[m][n][1] *= bfhi(ga[0]) * __builtin_amdgcn_rcpf(fmaxf(bfhi(gb[0]), 1e-30f));
;               acc[m][n][2] *= bflo(ga[1]) * __builtin_amdgcn_rcpf(fmaxf(bflo(gb[1]), 1e-30f));
;               acc[m][n][3] *= bfhi(ga[1]) * __builtin_amdgcn_rcpf(fmaxf(bfhi(gb[1]), 1e-30f));
;             }
;           }
	v_lshlrev_b32_e32 v166, 16, v178
	s_waitcnt lgkmcnt(0)
	v_lshlrev_b32_e32 v162, 16, v182
	v_and_b32_e32 v163, 0xffff0000, v182
	v_max_f32_e32 v162, v162, v162
	v_max_f32_e32 v163, v163, v163
	v_max_f32_e32 v162, 0xda24260, v162
	v_max_f32_e32 v163, 0xda24260, v163
	v_rcp_f32_e32 v162, v162
	v_rcp_f32_e32 v163, v163
	v_and_b32_e32 v167, 0xffff0000, v178
	v_pk_mul_f32 v[162:163], v[162:163], v[166:167]
	s_nop 0
	v_pk_mul_f32 v[10:11], v[10:11], v[162:163]
	v_lshlrev_b32_e32 v162, 16, v183
	v_and_b32_e32 v163, 0xffff0000, v183
	v_max_f32_e32 v162, v162, v162
	v_max_f32_e32 v163, v163, v163
	v_max_f32_e32 v162, 0xda24260, v162
	v_max_f32_e32 v163, 0xda24260, v163
	v_rcp_f32_e32 v162, v162
	v_rcp_f32_e32 v163, v163
	v_lshlrev_b32_e32 v166, 16, v179
	v_and_b32_e32 v167, 0xffff0000, v179
	v_pk_mul_f32 v[162:163], v[162:163], v[166:167]
	s_nop 0
	v_pk_mul_f32 v[12:13], v[12:13], v[162:163]
	v_add_u32_e32 v162, 6, v187
	v_bitop3_b32 v162, v162, v186, 7 bitop3:0x78
	v_lshlrev_b32_e32 v162, 4, v162
	v_add3_u32 v236, v162, v188, s28
	ds_read2st64_b64 v[186:189], v236 offset1:4
	ds_read2st64_b64 v[198:201], v236 offset0:8 offset1:12
	s_waitcnt lgkmcnt(1)
	v_lshlrev_b32_e32 v166, 16, v186
	s_waitcnt lgkmcnt(0)
	v_lshlrev_b32_e32 v162, 16, v198
	v_and_b32_e32 v163, 0xffff0000, v198
	v_max_f32_e32 v162, v162, v162
	v_max_f32_e32 v163, v163, v163
	v_max_f32_e32 v162, 0xda24260, v162
	v_max_f32_e32 v163, 0xda24260, v163
	v_rcp_f32_e32 v162, v162
	v_rcp_f32_e32 v163, v163
	v_and_b32_e32 v167, 0xffff0000, v186
	v_pk_mul_f32 v[162:163], v[162:163], v[166:167]
	s_nop 0
	v_pk_mul_f32 v[14:15], v[14:15], v[162:163]
	v_lshlrev_b32_e32 v162, 16, v199
	v_and_b32_e32 v163, 0xffff0000, v199
	v_max_f32_e32 v162, v162, v162
	v_max_f32_e32 v163, v163, v163
	v_max_f32_e32 v162, 0xda24260, v162
	v_max_f32_e32 v163, 0xda24260, v163
	v_rcp_f32_e32 v162, v162
	v_rcp_f32_e32 v163, v163
	v_lshlrev_b32_e32 v166, 16, v187
	v_and_b32_e32 v167, 0xffff0000, v187
	v_pk_mul_f32 v[162:163], v[162:163], v[166:167]
	s_nop 0
	v_pk_mul_f32 v[16:17], v[16:17], v[162:163]
	v_lshlrev_b32_e32 v162, 16, v168
	v_and_b32_e32 v163, 0xffff0000, v168
	v_max_f32_e32 v162, v162, v162
	v_max_f32_e32 v163, v163, v163
	v_max_f32_e32 v162, 0xda24260, v162
	v_max_f32_e32 v163, 0xda24260, v163
	v_rcp_f32_e32 v162, v162
	v_rcp_f32_e32 v163, v163
	v_lshlrev_b32_e32 v166, 16, v164
	v_and_b32_e32 v167, 0xffff0000, v164
	v_lshlrev_b32_e32 v164, 16, v165
	v_pk_mul_f32 v[162:163], v[162:163], v[166:167]
	v_and_b32_e32 v165, 0xffff0000, v165
	v_pk_mul_f32 v[18:19], v[18:19], v[162:163]
	v_lshlrev_b32_e32 v162, 16, v169
	v_and_b32_e32 v163, 0xffff0000, v169
	v_max_f32_e32 v162, v162, v162
	v_max_f32_e32 v163, v163, v163
	v_max_f32_e32 v162, 0xda24260, v162
	v_max_f32_e32 v163, 0xda24260, v163
	v_rcp_f32_e32 v162, v162
	v_rcp_f32_e32 v163, v163
	s_nop 0
	v_pk_mul_f32 v[162:163], v[162:163], v[164:165]
	s_nop 0
	v_pk_mul_f32 v[20:21], v[20:21], v[162:163]
	v_lshlrev_b32_e32 v162, 16, v176
	v_and_b32_e32 v163, 0xffff0000, v176
	v_max_f32_e32 v162, v162, v162
	v_max_f32_e32 v163, v163, v163
	v_max_f32_e32 v162, 0xda24260, v162
	v_max_f32_e32 v163, 0xda24260, v163
	v_rcp_f32_e32 v162, v162
	v_rcp_f32_e32 v163, v163
	v_lshlrev_b32_e32 v164, 16, v172
	v_and_b32_e32 v165, 0xffff0000, v172
	v_pk_mul_f32 v[162:163], v[162:163], v[164:165]
	s_nop 0
	v_pk_mul_f32 v[26:27], v[26:27], v[162:163]
	v_lshlrev_b32_e32 v162, 16, v177
	v_and_b32_e32 v163, 0xffff0000, v177
	v_max_f32_e32 v162, v162, v162
	v_max_f32_e32 v163, v163, v163
	v_max_f32_e32 v162, 0xda24260, v162
	v_max_f32_e32 v163, 0xda24260, v163
	v_rcp_f32_e32 v162, v162
	v_rcp_f32_e32 v163, v163
	v_lshlrev_b32_e32 v164, 16, v173
	v_and_b32_e32 v165, 0xffff0000, v173
	v_pk_mul_f32 v[162:163], v[162:163], v[164:165]
	s_nop 0
	v_pk_mul_f32 v[28:29], v[28:29], v[162:163]
	v_lshlrev_b32_e32 v162, 16, v184
	v_and_b32_e32 v163, 0xffff0000, v184
	v_max_f32_e32 v162, v162, v162
	v_max_f32_e32 v163, v163, v163
	v_max_f32_e32 v162, 0xda24260, v162
	v_max_f32_e32 v163, 0xda24260, v163
	v_rcp_f32_e32 v162, v162
	v_rcp_f32_e32 v163, v163
	v_lshlrev_b32_e32 v164, 16, v180
	v_and_b32_e32 v165, 0xffff0000, v180
	v_pk_mul_f32 v[162:163], v[162:163], v[164:165]
	s_nop 0
	v_pk_mul_f32 v[34:35], v[34:35], v[162:163]
	v_lshlrev_b32_e32 v162, 16, v185
	v_and_b32_e32 v163, 0xffff0000, v185
	v_max_f32_e32 v162, v162, v162
	v_max_f32_e32 v163, v163, v163
	v_max_f32_e32 v162, 0xda24260, v162
	v_max_f32_e32 v163, 0xda24260, v163
	v_rcp_f32_e32 v162, v162
	v_rcp_f32_e32 v163, v163
	v_lshlrev_b32_e32 v164, 16, v181
	v_and_b32_e32 v165, 0xffff0000, v181
	v_pk_mul_f32 v[162:163], v[162:163], v[164:165]
	s_nop 0
	v_pk_mul_f32 v[36:37], v[36:37], v[162:163]
	v_lshlrev_b32_e32 v162, 16, v200
	v_and_b32_e32 v163, 0xffff0000, v200
	v_max_f32_e32 v162, v162, v162
	v_max_f32_e32 v163, v163, v163
	v_max_f32_e32 v162, 0xda24260, v162
	v_max_f32_e32 v163, 0xda24260, v163
	v_rcp_f32_e32 v162, v162
	v_rcp_f32_e32 v163, v163
	v_lshlrev_b32_e32 v164, 16, v188
	v_and_b32_e32 v165, 0xffff0000, v188
	v_pk_mul_f32 v[162:163], v[162:163], v[164:165]
	s_nop 0
	v_pk_mul_f32 v[42:43], v[42:43], v[162:163]
	v_lshlrev_b32_e32 v162, 16, v201
	v_and_b32_e32 v163, 0xffff0000, v201
	v_max_f32_e32 v162, v162, v162
	v_max_f32_e32 v163, v163, v163
	v_max_f32_e32 v162, 0xda24260, v162
	v_max_f32_e32 v163, 0xda24260, v163
	v_rcp_f32_e32 v162, v162
	v_rcp_f32_e32 v163, v163
	v_lshlrev_b32_e32 v164, 16, v189
	v_and_b32_e32 v165, 0xffff0000, v189
	v_pk_mul_f32 v[162:163], v[162:163], v[164:165]
	s_nop 0
	v_pk_mul_f32 v[44:45], v[44:45], v[162:163]
	s_waitcnt vmcnt(0)
; __device__ __forceinline__ float bflo(unsigned w) { return __uint_as_float(w << 16); }
; __device__ __forceinline__ float bfhi(unsigned w) { return __uint_as_float(w & 0xffff0000u); }
; #define SCHED() __builtin_amdgcn_sched_barrier(0)
; template <int MODE>
; __device__ __forceinline__ void gemm_phase(const Params& p, int l, int cb, char* shm) {
;     ...
;         for (int q = 0; q < 4; ++q) {
; #pragma unroll
;           for (int i = 0; i < 4; ++i) {
;             const int so = (lrow + 8 * i) * 128 + ((lch ^ lrow) << 4);
;             *(u32x4*)(est + so) = ra[i]; *(u32x4*)(est + 4096 + so) = rb[i];
;           }
;           SCHED();
;           if (q < 3) {
; #pragma unroll
;             for (int i = 0; i < 4; ++i) { ra[i] = *(const u32x4*)(gsrc + (size_t)(32 * (q + 1) + 8 * i) * PW + PC_GA); rb[i] = *(const u32x4*)(gsrc + (size_t)(32 * (q + 1) + 8 * i) * PW + PC_GB); }
;           }
;           SCHED();
; #pragma unroll
;           for (int mm = 0; mm < 2; ++mm) {
;             const int m = q * 2 + mm, row = mm * 16 + fr;
; #pragma unroll
;             for (int n = 0; n < 4; ++n) {
;               const int off = row * 128 + (((n * 2 + (fq >> 1)) ^ (row & 7)) << 4) + (fq & 1) * 8;
;               const u32x2 ga = *(const u32x2*)(est + off), gb = *(const u32x2*)(est + 4096 + off);
;               acc[m][n][0] *= bflo(ga[0]) * __builtin_amdgcn_rcpf(fmaxf(bflo(gb[0]), 1e-30f));
;               acc[m][n][1] *= bfhi(ga[0]) * __builtin_amdgcn_rcpf(fmaxf(bfhi(gb[0]), 1e-30f));
;               acc[m][n][2] *= bflo(ga[1]) * __builtin_amdgcn_rcpf(fmaxf(bflo(gb[1]), 1e-30f));
;               acc[m][n][3] *= bfhi(ga[1]) * __builtin_amdgcn_rcpf(fmaxf(bfhi(gb[1]), 1e-30f));
;             }
;           }
	ds_write_b128 v238, v[158:161]
	ds_write_b128 v238, v[154:157] offset:4096
	ds_write_b128 v238, v[150:153] offset:1024
	ds_write_b128 v238, v[146:149] offset:5120
	ds_write_b128 v238, v[142:145] offset:2048
	ds_write_b128 v238, v[138:141] offset:6144
	ds_write_b128 v238, v[134:137] offset:3072
	ds_write_b128 v238, v[130:133] offset:7168
	s_mov_b32 s0, 0xcd000
	v_add_co_u32_e32 v130, vcc, s0, v232
	s_mov_b32 s0, 0xcc000
	s_nop 0
	v_addc_co_u32_e32 v131, vcc, 0, v233, vcc
	v_add_co_u32_e32 v134, vcc, s0, v232
	s_mov_b32 s0, 0xba000
	s_nop 0
	v_addc_co_u32_e32 v135, vcc, 0, v233, vcc
	v_add_co_u32_e32 v142, vcc, s0, v232
	s_mov_b32 s0, 0xa8000
	s_nop 0
	v_addc_co_u32_e32 v143, vcc, 0, v233, vcc
	v_add_co_u32_e32 v146, vcc, s0, v232
	s_mov_b32 s0, 0xa7000
	s_nop 0
	v_addc_co_u32_e32 v147, vcc, 0, v233, vcc
	v_add_co_u32_e32 v150, vcc, s0, v232
	s_mov_b32 s0, 0x95000
	s_nop 0
	v_addc_co_u32_e32 v151, vcc, 0, v233, vcc
	v_add_co_u32_e32 v158, vcc, s0, v232
	global_load_dwordx4 v[130:133], v[130:131], off offset:1280
	s_nop 0
	global_load_dwordx4 v[134:137], v[134:135], off offset:3328
	v_addc_co_u32_e32 v159, vcc, 0, v233, vcc
	global_load_dwordx4 v[138:141], v[142:143], off offset:3328
	s_nop 0
	global_load_dwordx4 v[142:145], v[142:143], off offset:1280
	s_nop 0
	global_load_dwordx4 v[146:149], v[146:147], off offset:1280
	s_nop 0
	global_load_dwordx4 v[150:153], v[150:151], off offset:3328
	s_nop 0
	global_load_dwordx4 v[154:157], v[158:159], off offset:3328
	s_nop 0
	global_load_dwordx4 v[158:161], v[158:159], off offset:1280
	ds_read2st64_b64 v[162:165], v244 offset1:4
	ds_read2st64_b64 v[166:169], v244 offset0:8 offset1:12
	s_waitcnt lgkmcnt(1)
	v_lshlrev_b32_e32 v172, 16, v162
	s_waitcnt lgkmcnt(0)
	v_lshlrev_b32_e32 v170, 16, v166
	v_and_b32_e32 v166, 0xffff0000, v166
	v_max_f32_e32 v170, v170, v170
	v_max_f32_e32 v166, v166, v166
	v_max_f32_e32 v170, 0xda24260, v170
	v_max_f32_e32 v166, 0xda24260, v166
	v_and_b32_e32 v173, 0xffff0000, v162
	v_lshlrev_b32_e32 v162, 16, v167
	v_rcp_f32_e32 v170, v170
	v_rcp_f32_e32 v171, v166
	v_max_f32_e32 v162, v162, v162
	v_max_f32_e32 v162, 0xda24260, v162
	v_rcp_f32_e32 v166, v162
	v_and_b32_e32 v162, 0xffff0000, v167
	v_max_f32_e32 v162, v162, v162
	v_pk_mul_f32 v[170:171], v[170:171], v[172:173]
	v_max_f32_e32 v162, 0xda24260, v162
	v_pk_mul_f32 v[54:55], v[54:55], v[170:171]
	v_rcp_f32_e32 v167, v162
	ds_read2st64_b64 v[170:173], v245 offset1:4
	ds_read2st64_b64 v[176:179], v245 offset0:8 offset1:12
	v_lshlrev_b32_e32 v162, 16, v163
	v_and_b32_e32 v163, 0xffff0000, v163
	v_pk_mul_f32 v[162:163], v[166:167], v[162:163]
	s_waitcnt lgkmcnt(1)
	v_lshlrev_b32_e32 v166, 16, v170
	v_pk_mul_f32 v[56:57], v[56:57], v[162:163]
	s_waitcnt lgkmcnt(0)
	v_lshlrev_b32_e32 v162, 16, v176
	v_and_b32_e32 v163, 0xffff0000, v176
	v_max_f32_e32 v162, v162, v162
	v_max_f32_e32 v163, v163, v163
	v_max_f32_e32 v162, 0xda24260, v162
	v_max_f32_e32 v163, 0xda24260, v163
	v_rcp_f32_e32 v162, v162
	v_rcp_f32_e32 v163, v163
	v_and_b32_e32 v167, 0xffff0000, v170
	v_pk_mul_f32 v[162:163], v[162:163], v[166:167]
	s_nop 0
	v_pk_mul_f32 v[62:63], v[62:63], v[162:163]
	v_lshlrev_b32_e32 v162, 16, v177
	v_and_b32_e32 v163, 0xffff0000, v177
	v_max_f32_e32 v162, v162, v162
	v_max_f32_e32 v163, v163, v163
	v_max_f32_e32 v162, 0xda24260, v162
	v_max_f32_e32 v163, 0xda24260, v163
	v_rcp_f32_e32 v162, v162
	v_rcp_f32_e32 v163, v163
	ds_read2st64_b64 v[174:177], v246 offset1:4
	ds_read2st64_b64 v[182:185], v246 offset0:8 offset1:12
	v_lshlrev_b32_e32 v166, 16, v171
	v_and_b32_e32 v167, 0xffff0000, v171
	v_pk_mul_f32 v[162:163], v[162:163], v[166:167]
	s_waitcnt lgkmcnt(1)
	v_lshlrev_b32_e32 v166, 16, v174
	v_pk_mul_f32 v[64:65], v[64:65], v[162:163]
	s_waitcnt lgkmcnt(0)
	v_lshlrev_b32_e32 v162, 16, v182
	v_and_b32_e32 v163, 0xffff0000, v182
	v_max_f32_e32 v162, v162, v162
	v_max_f32_e32 v163, v163, v163
	v_max_f32_e32 v162, 0xda24260, v162
	v_max_f32_e32 v163, 0xda24260, v163
	v_rcp_f32_e32 v162, v162
	v_rcp_f32_e32 v163, v163
	v_and_b32_e32 v167, 0xffff0000, v174
	v_pk_mul_f32 v[162:163], v[162:163], v[166:167]
	s_nop 0
	v_pk_mul_f32 v[70:71], v[70:71], v[162:163]
	v_lshlrev_b32_e32 v162, 16, v183
	v_and_b32_e32 v163, 0xffff0000, v183
	v_max_f32_e32 v162, v162, v162
	v_max_f32_e32 v163, v163, v163
	v_max_f32_e32 v162, 0xda24260, v162
	v_max_f32_e32 v163, 0xda24260, v163
	v_rcp_f32_e32 v162, v162
	v_rcp_f32_e32 v163, v163
	ds_read2st64_b64 v[180:183], v236 offset1:4
	ds_read2st64_b64 v[186:189], v236 offset0:8 offset1:12
	v_lshlrev_b32_e32 v166, 16, v175
	v_and_b32_e32 v167, 0xffff0000, v175
	v_pk_mul_f32 v[162:163], v[162:163], v[166:167]
	s_waitcnt lgkmcnt(1)
	v_lshlrev_b32_e32 v166, 16, v180
	v_pk_mul_f32 v[72:73], v[72:73], v[162:163]
	s_waitcnt lgkmcnt(0)
; __device__ __forceinline__ float bflo(unsigned w) { return __uint_as_float(w << 16); }
; __device__ __forceinline__ float bfhi(unsigned w) { return __uint_as_float(w & 0xffff0000u); }
; #define SCHED() __builtin_amdgcn_sched_barrier(0)
; template <int MODE>
; __device__ __forceinline__ void gemm_phase(const Params& p, int l, int cb, char* shm) {
;     ...
;         for (int q = 0; q < 4; ++q) {
; #pragma unroll
;           for (int i = 0; i < 4; ++i) {
;             const int so = (lrow + 8 * i) * 128 + ((lch ^ lrow) << 4);
;             *(u32x4*)(est + so) = ra[i]; *(u32x4*)(est + 4096 + so) = rb[i];
;           }
;           SCHED();
;           if (q < 3) {
; #pragma unroll
;             for (int i = 0; i < 4; ++i) { ra[i] = *(const u32x4*)(gsrc + (size_t)(32 * (q + 1) + 8 * i) * PW + PC_GA); rb[i] = *(const u32x4*)(gsrc + (size_t)(32 * (q + 1) + 8 * i) * PW + PC_GB); }
;           }
;           SCHED();
; #pragma unroll
;           for (int mm = 0; mm < 2; ++mm) {
;             const int m = q * 2 + mm, row = mm * 16 + fr;
; #pragma unroll
;             for (int n = 0; n < 4; ++n) {
;               const int off = row * 128 + (((n * 2 + (fq >> 1)) ^ (row & 7)) << 4) + (fq & 1) * 8;
;               const u32x2 ga = *(const u32x2*)(est + off), gb = *(const u32x2*)(est + 4096 + off);
;               acc[m][n][0] *= bflo(ga[0]) * __builtin_amdgcn_rcpf(fmaxf(bflo(gb[0]), 1e-30f));
;               acc[m][n][1] *= bfhi(ga[0]) * __builtin_amdgcn_rcpf(fmaxf(bfhi(gb[0]), 1e-30f));
;               acc[m][n][2] *= bflo(ga[1]) * __builtin_amdgcn_rcpf(fmaxf(bflo(gb[1]), 1e-30f));
;               acc[m][n][3] *= bfhi(ga[1]) * __builtin_amdgcn_rcpf(fmaxf(bfhi(gb[1]), 1e-30f));
;             }
;           }
	v_lshlrev_b32_e32 v162, 16, v186
	v_and_b32_e32 v163, 0xffff0000, v186
	v_max_f32_e32 v162, v162, v162
	v_max_f32_e32 v163, v163, v163
	v_max_f32_e32 v162, 0xda24260, v162
	v_max_f32_e32 v163, 0xda24260, v163
	v_rcp_f32_e32 v162, v162
	v_rcp_f32_e32 v163, v163
	v_and_b32_e32 v167, 0xffff0000, v180
	v_pk_mul_f32 v[162:163], v[162:163], v[166:167]
	s_nop 0
	v_pk_mul_f32 v[74:75], v[74:75], v[162:163]
	v_lshlrev_b32_e32 v162, 16, v187
	v_and_b32_e32 v163, 0xffff0000, v187
	v_max_f32_e32 v162, v162, v162
	v_max_f32_e32 v163, v163, v163
	v_max_f32_e32 v162, 0xda24260, v162
	v_max_f32_e32 v163, 0xda24260, v163
	v_rcp_f32_e32 v162, v162
	v_rcp_f32_e32 v163, v163
	v_lshlrev_b32_e32 v166, 16, v181
	v_and_b32_e32 v167, 0xffff0000, v181
	v_pk_mul_f32 v[162:163], v[162:163], v[166:167]
	s_nop 0
	v_pk_mul_f32 v[76:77], v[76:77], v[162:163]
	v_lshlrev_b32_e32 v162, 16, v168
	v_and_b32_e32 v163, 0xffff0000, v168
	v_max_f32_e32 v162, v162, v162
	v_max_f32_e32 v163, v163, v163
	v_max_f32_e32 v162, 0xda24260, v162
	v_max_f32_e32 v163, 0xda24260, v163
	v_rcp_f32_e32 v162, v162
	v_rcp_f32_e32 v163, v163
	v_lshlrev_b32_e32 v166, 16, v164
	v_and_b32_e32 v167, 0xffff0000, v164
	v_lshlrev_b32_e32 v164, 16, v165
	v_pk_mul_f32 v[162:163], v[162:163], v[166:167]
	v_and_b32_e32 v165, 0xffff0000, v165
	v_pk_mul_f32 v[82:83], v[82:83], v[162:163]
	v_lshlrev_b32_e32 v162, 16, v169
	v_and_b32_e32 v163, 0xffff0000, v169
	v_max_f32_e32 v162, v162, v162
	v_max_f32_e32 v163, v163, v163
	v_max_f32_e32 v162, 0xda24260, v162
	v_max_f32_e32 v163, 0xda24260, v163
	v_rcp_f32_e32 v162, v162
	v_rcp_f32_e32 v163, v163
	s_nop 0
	v_pk_mul_f32 v[162:163], v[162:163], v[164:165]
	s_nop 0
	v_pk_mul_f32 v[84:85], v[84:85], v[162:163]
	v_lshlrev_b32_e32 v162, 16, v178
	v_and_b32_e32 v163, 0xffff0000, v178
	v_max_f32_e32 v162, v162, v162
	v_max_f32_e32 v163, v163, v163
	v_max_f32_e32 v162, 0xda24260, v162
	v_max_f32_e32 v163, 0xda24260, v163
	v_rcp_f32_e32 v162, v162
	v_rcp_f32_e32 v163, v163
	v_lshlrev_b32_e32 v164, 16, v172
	v_and_b32_e32 v165, 0xffff0000, v172
	v_pk_mul_f32 v[162:163], v[162:163], v[164:165]
	s_nop 0
	v_pk_mul_f32 v[90:91], v[90:91], v[162:163]
	v_lshlrev_b32_e32 v162, 16, v179
	v_and_b32_e32 v163, 0xffff0000, v179
	v_max_f32_e32 v162, v162, v162
	v_max_f32_e32 v163, v163, v163
	v_max_f32_e32 v162, 0xda24260, v162
	v_max_f32_e32 v163, 0xda24260, v163
	v_rcp_f32_e32 v162, v162
	v_rcp_f32_e32 v163, v163
	v_lshlrev_b32_e32 v164, 16, v173
	v_and_b32_e32 v165, 0xffff0000, v173
	v_pk_mul_f32 v[162:163], v[162:163], v[164:165]
	s_nop 0
	v_pk_mul_f32 v[92:93], v[92:93], v[162:163]
	v_lshlrev_b32_e32 v162, 16, v184
	v_and_b32_e32 v163, 0xffff0000, v184
	v_max_f32_e32 v162, v162, v162
	v_max_f32_e32 v163, v163, v163
	v_max_f32_e32 v162, 0xda24260, v162
	v_max_f32_e32 v163, 0xda24260, v163
	v_rcp_f32_e32 v162, v162
	v_rcp_f32_e32 v163, v163
	v_lshlrev_b32_e32 v164, 16, v176
	v_and_b32_e32 v165, 0xffff0000, v176
	v_pk_mul_f32 v[162:163], v[162:163], v[164:165]
	s_nop 0
	v_pk_mul_f32 v[102:103], v[102:103], v[162:163]
	v_lshlrev_b32_e32 v162, 16, v185
	v_and_b32_e32 v163, 0xffff0000, v185
	v_max_f32_e32 v162, v162, v162
	v_max_f32_e32 v163, v163, v163
	v_max_f32_e32 v162, 0xda24260, v162
	v_max_f32_e32 v163, 0xda24260, v163
	v_rcp_f32_e32 v162, v162
	v_rcp_f32_e32 v163, v163
	v_lshlrev_b32_e32 v164, 16, v177
	v_and_b32_e32 v165, 0xffff0000, v177
	v_pk_mul_f32 v[162:163], v[162:163], v[164:165]
	s_nop 0
	v_pk_mul_f32 v[104:105], v[104:105], v[162:163]
	v_lshlrev_b32_e32 v162, 16, v188
	v_and_b32_e32 v163, 0xffff0000, v188
	v_max_f32_e32 v162, v162, v162
	v_max_f32_e32 v163, v163, v163
	v_max_f32_e32 v162, 0xda24260, v162
	v_max_f32_e32 v163, 0xda24260, v163
	v_rcp_f32_e32 v162, v162
	v_rcp_f32_e32 v163, v163
	v_lshlrev_b32_e32 v164, 16, v182
	v_and_b32_e32 v165, 0xffff0000, v182
	v_pk_mul_f32 v[162:163], v[162:163], v[164:165]
	s_nop 0
	v_pk_mul_f32 v[114:115], v[114:115], v[162:163]
	v_lshlrev_b32_e32 v162, 16, v189
	v_and_b32_e32 v163, 0xffff0000, v189
	v_max_f32_e32 v162, v162, v162
	v_max_f32_e32 v163, v163, v163
	v_max_f32_e32 v162, 0xda24260, v162
	v_max_f32_e32 v163, 0xda24260, v163
	v_rcp_f32_e32 v162, v162
	v_rcp_f32_e32 v163, v163
	v_lshlrev_b32_e32 v164, 16, v183
	v_and_b32_e32 v165, 0xffff0000, v183
	v_pk_mul_f32 v[162:163], v[162:163], v[164:165]
	s_nop 0
	v_pk_mul_f32 v[116:117], v[116:117], v[162:163]
	s_waitcnt vmcnt(0)
	ds_write_b128 v238, v[158:161]
	ds_write_b128 v238, v[154:157] offset:4096
	ds_write_b128 v238, v[150:153] offset:1024
	ds_write_b128 v238, v[146:149] offset:5120
	ds_write_b128 v238, v[142:145] offset:2048
	ds_write_b128 v238, v[138:141] offset:6144
	ds_write_b128 v238, v[134:137] offset:3072
	ds_write_b128 v238, v[130:133] offset:7168
	s_mov_b32 s0, 0x117000
	v_add_co_u32_e32 v130, vcc, s0, v232
	s_mov_b32 s0, 0x116000
	s_nop 0
	v_addc_co_u32_e32 v131, vcc, 0, v233, vcc
	v_add_co_u32_e32 v132, vcc, s0, v232
	s_mov_b32 s0, 0x104000
	s_nop 0
	v_addc_co_u32_e32 v133, vcc, 0, v233, vcc
	global_load_dwordx4 v[146:149], v[130:131], off offset:1280
	global_load_dwordx4 v[150:153], v[132:133], off offset:3328
	v_add_co_u32_e32 v130, vcc, s0, v232
	s_mov_b32 s0, 0xf2000
	s_nop 0
	v_addc_co_u32_e32 v131, vcc, 0, v233, vcc
	global_load_dwordx4 v[154:157], v[130:131], off offset:3328
	global_load_dwordx4 v[158:161], v[130:131], off offset:1280
	v_add_co_u32_e32 v130, vcc, s0, v232
	s_mov_b32 s0, 0xf1000
	s_nop 0
	v_addc_co_u32_e32 v131, vcc, 0, v233, vcc
	v_add_co_u32_e32 v132, vcc, s0, v232
	s_mov_b32 s0, 0xdf000
	s_nop 0
	v_addc_co_u32_e32 v133, vcc, 0, v233, vcc
	global_load_dwordx4 v[162:165], v[130:131], off offset:1280
	global_load_dwordx4 v[166:169], v[132:133], off offset:3328
	v_add_co_u32_e32 v130, vcc, s0, v232
	s_nop 1
	v_addc_co_u32_e32 v131, vcc, 0, v233, vcc
	global_load_dwordx4 v[170:173], v[130:131], off offset:3328
	global_load_dwordx4 v[174:177], v[130:131], off offset:1280
	ds_read2st64_b64 v[130:133], v244 offset1:4
	ds_read2st64_b64 v[134:137], v244 offset0:8 offset1:12
	ds_read2st64_b64 v[138:141], v245 offset1:4
	ds_read2st64_b64 v[142:145], v245 offset0:8 offset1:12
	ds_read2st64_b64 v[178:181], v246 offset1:4
	ds_read2st64_b64 v[182:185], v246 offset0:8 offset1:12
	ds_read2st64_b64 v[186:189], v236 offset1:4
	ds_read2st64_b64 v[198:201], v236 offset0:8 offset1:12
	s_waitcnt vmcnt(0)
; __device__ __forceinline__ float bflo(unsigned w) { return __uint_as_float(w << 16); }
; __device__ __forceinline__ float bfhi(unsigned w) { return __uint_as_float(w & 0xffff0000u); }
; #define SCHED() __builtin_amdgcn_sched_barrier(0)
; template <int MODE>
; __device__ __forceinline__ void gemm_phase(const Params& p, int l, int cb, char* shm) {
;     ...
;         for (int q = 0; q < 4; ++q) {
; #pragma unroll
;           for (int i = 0; i < 4; ++i) {
;             const int so = (lrow + 8 * i) * 128 + ((lch ^ lrow) << 4);
;             *(u32x4*)(est + so) = ra[i]; *(u32x4*)(est + 4096 + so) = rb[i];
;           }
;           SCHED();
;           if (q < 3) {
; #pragma unroll
;             for (int i = 0; i < 4; ++i) { ra[i] = *(const u32x4*)(gsrc + (size_t)(32 * (q + 1) + 8 * i) * PW + PC_GA); rb[i] = *(const u32x4*)(gsrc + (size_t)(32 * (q + 1) + 8 * i) * PW + PC_GB); }
;           }
;           SCHED();
; #pragma unroll
;           for (int mm = 0; mm < 2; ++mm) {
;             const int m = q * 2 + mm, row = mm * 16 + fr;
; #pragma unroll
;             for (int n = 0; n < 4; ++n) {
;               const int off = row * 128 + (((n * 2 + (fq >> 1)) ^ (row & 7)) << 4) + (fq & 1) * 8;
;               const u32x2 ga = *(const u32x2*)(est + off), gb = *(const u32x2*)(est + 4096 + off);
;               acc[m][n][0] *= bflo(ga[0]) * __builtin_amdgcn_rcpf(fmaxf(bflo(gb[0]), 1e-30f));
;               acc[m][n][1] *= bfhi(ga[0]) * __builtin_amdgcn_rcpf(fmaxf(bfhi(gb[0]), 1e-30f));
;               acc[m][n][2] *= bflo(ga[1]) * __builtin_amdgcn_rcpf(fmaxf(bflo(gb[1]), 1e-30f));
;               acc[m][n][3] *= bfhi(ga[1]) * __builtin_amdgcn_rcpf(fmaxf(bfhi(gb[1]), 1e-30f));
;             }
;           }
	ds_write_b128 v238, v[174:177]
	ds_write_b128 v238, v[170:173] offset:4096
	ds_write_b128 v238, v[166:169] offset:1024
	ds_write_b128 v238, v[162:165] offset:5120
	ds_write_b128 v238, v[158:161] offset:2048
	ds_write_b128 v238, v[154:157] offset:6144
	ds_write_b128 v238, v[150:153] offset:3072
	ds_write_b128 v238, v[146:149] offset:7168
	s_waitcnt lgkmcnt(8)
	v_lshlrev_b32_e32 v146, 16, v200
	v_and_b32_e32 v147, 0xffff0000, v200
	v_max_f32_e32 v146, v146, v146
	v_max_f32_e32 v147, v147, v147
	v_max_f32_e32 v146, 0xda24260, v146
	v_max_f32_e32 v147, 0xda24260, v147
	v_rcp_f32_e32 v146, v146
	v_rcp_f32_e32 v147, v147
	v_lshlrev_b32_e32 v148, 16, v188
	v_and_b32_e32 v149, 0xffff0000, v188
	v_pk_mul_f32 v[146:147], v[146:147], v[148:149]
	v_lshlrev_b32_e32 v148, 16, v201
	v_and_b32_e32 v149, 0xffff0000, v201
	v_max_f32_e32 v148, v148, v148
	v_max_f32_e32 v149, v149, v149
	v_max_f32_e32 v148, 0xda24260, v148
	v_max_f32_e32 v149, 0xda24260, v149
	v_rcp_f32_e32 v148, v148
	v_rcp_f32_e32 v149, v149
	v_pk_mul_f32 v[98:99], v[98:99], v[146:147]
	v_lshlrev_b32_e32 v146, 16, v189
	v_and_b32_e32 v147, 0xffff0000, v189
	v_pk_mul_f32 v[146:147], v[148:149], v[146:147]
	v_lshlrev_b32_e32 v148, 16, v184
	v_and_b32_e32 v149, 0xffff0000, v184
	v_max_f32_e32 v148, v148, v148
	v_max_f32_e32 v149, v149, v149
	v_max_f32_e32 v148, 0xda24260, v148
	v_max_f32_e32 v149, 0xda24260, v149
	v_rcp_f32_e32 v148, v148
	v_rcp_f32_e32 v149, v149
	v_pk_mul_f32 v[100:101], v[100:101], v[146:147]
	v_lshlrev_b32_e32 v146, 16, v180
	v_and_b32_e32 v147, 0xffff0000, v180
	v_pk_mul_f32 v[146:147], v[148:149], v[146:147]
	v_lshlrev_b32_e32 v148, 16, v185
	v_and_b32_e32 v149, 0xffff0000, v185
	v_max_f32_e32 v148, v148, v148
	v_max_f32_e32 v149, v149, v149
	v_max_f32_e32 v148, 0xda24260, v148
	v_max_f32_e32 v149, 0xda24260, v149
	v_rcp_f32_e32 v148, v148
	v_rcp_f32_e32 v149, v149
	v_pk_mul_f32 v[110:111], v[110:111], v[146:147]
	v_lshlrev_b32_e32 v146, 16, v181
	v_and_b32_e32 v147, 0xffff0000, v181
	v_pk_mul_f32 v[146:147], v[148:149], v[146:147]
	v_lshlrev_b32_e32 v148, 16, v144
	v_and_b32_e32 v144, 0xffff0000, v144
	v_pk_mul_f32 v[112:113], v[112:113], v[146:147]
	v_lshlrev_b32_e32 v146, 16, v140
	v_and_b32_e32 v147, 0xffff0000, v140
	v_lshlrev_b32_e32 v140, 16, v145
	v_max_f32_e32 v144, v144, v144
	v_max_f32_e32 v140, v140, v140
	v_max_f32_e32 v144, 0xda24260, v144
	v_max_f32_e32 v140, 0xda24260, v140
	v_rcp_f32_e32 v149, v144
	v_rcp_f32_e32 v144, v140
	v_and_b32_e32 v140, 0xffff0000, v145
	v_max_f32_e32 v140, v140, v140
	v_max_f32_e32 v140, 0xda24260, v140
	v_rcp_f32_e32 v145, v140
	v_lshlrev_b32_e32 v140, 16, v141
	v_and_b32_e32 v141, 0xffff0000, v141
	v_max_f32_e32 v148, v148, v148
	v_pk_mul_f32 v[140:141], v[144:145], v[140:141]
	v_lshlrev_b32_e32 v144, 16, v136
	v_and_b32_e32 v136, 0xffff0000, v136
	v_pk_mul_f32 v[124:125], v[124:125], v[140:141]
	v_lshlrev_b32_e32 v140, 16, v132
	v_and_b32_e32 v141, 0xffff0000, v132
	v_lshlrev_b32_e32 v132, 16, v137
	v_max_f32_e32 v136, v136, v136
	v_max_f32_e32 v132, v132, v132
	v_max_f32_e32 v136, 0xda24260, v136
	v_max_f32_e32 v132, 0xda24260, v132
	v_rcp_f32_e32 v145, v136
	v_rcp_f32_e32 v136, v132
	v_and_b32_e32 v132, 0xffff0000, v137
	v_max_f32_e32 v132, v132, v132
	v_max_f32_e32 v132, 0xda24260, v132
	v_rcp_f32_e32 v137, v132
	v_lshlrev_b32_e32 v132, 16, v133
	v_and_b32_e32 v133, 0xffff0000, v133
	v_max_f32_e32 v144, v144, v144
	v_pk_mul_f32 v[132:133], v[136:137], v[132:133]
	v_lshlrev_b32_e32 v136, 16, v198
	v_and_b32_e32 v137, 0xffff0000, v198
	v_max_f32_e32 v136, v136, v136
	v_max_f32_e32 v137, v137, v137
	v_max_f32_e32 v136, 0xda24260, v136
	v_max_f32_e32 v137, 0xda24260, v137
	v_rcp_f32_e32 v136, v136
	v_rcp_f32_e32 v137, v137
	v_pk_mul_f32 v[128:129], v[128:129], v[132:133]
	v_lshlrev_b32_e32 v132, 16, v186
	v_and_b32_e32 v133, 0xffff0000, v186
	v_pk_mul_f32 v[132:133], v[136:137], v[132:133]
	v_lshlrev_b32_e32 v136, 16, v199
	v_and_b32_e32 v137, 0xffff0000, v199
	v_max_f32_e32 v136, v136, v136
	v_max_f32_e32 v137, v137, v137
	v_max_f32_e32 v136, 0xda24260, v136
	v_max_f32_e32 v137, 0xda24260, v137
	v_rcp_f32_e32 v136, v136
	v_rcp_f32_e32 v137, v137
	v_pk_mul_f32 v[118:119], v[118:119], v[132:133]
	v_lshlrev_b32_e32 v132, 16, v187
	v_and_b32_e32 v133, 0xffff0000, v187
	v_pk_mul_f32 v[132:133], v[136:137], v[132:133]
	v_lshlrev_b32_e32 v136, 16, v182
	v_and_b32_e32 v137, 0xffff0000, v182
	v_max_f32_e32 v136, v136, v136
	v_max_f32_e32 v137, v137, v137
	v_max_f32_e32 v136, 0xda24260, v136
	v_max_f32_e32 v137, 0xda24260, v137
	v_rcp_f32_e32 v136, v136
	v_rcp_f32_e32 v137, v137
	v_pk_mul_f32 v[120:121], v[120:121], v[132:133]
	v_lshlrev_b32_e32 v132, 16, v178
	v_and_b32_e32 v133, 0xffff0000, v178
	v_pk_mul_f32 v[132:133], v[136:137], v[132:133]
	v_lshlrev_b32_e32 v136, 16, v183
	v_and_b32_e32 v137, 0xffff0000, v183
	v_max_f32_e32 v136, v136, v136
	v_max_f32_e32 v137, v137, v137
	v_max_f32_e32 v136, 0xda24260, v136
	v_max_f32_e32 v137, 0xda24260, v137
	v_rcp_f32_e32 v136, v136
	v_rcp_f32_e32 v137, v137
	v_pk_mul_f32 v[106:107], v[106:107], v[132:133]
	v_lshlrev_b32_e32 v132, 16, v179
	v_and_b32_e32 v133, 0xffff0000, v179
	v_pk_mul_f32 v[132:133], v[136:137], v[132:133]
	v_lshlrev_b32_e32 v136, 16, v142
	v_and_b32_e32 v137, 0xffff0000, v142
	v_max_f32_e32 v136, v136, v136
	v_max_f32_e32 v137, v137, v137
	v_max_f32_e32 v136, 0xda24260, v136
	v_max_f32_e32 v137, 0xda24260, v137
	v_rcp_f32_e32 v136, v136
	v_rcp_f32_e32 v137, v137
	v_pk_mul_f32 v[108:109], v[108:109], v[132:133]
	v_lshlrev_b32_e32 v132, 16, v138
	v_and_b32_e32 v133, 0xffff0000, v138
	v_pk_mul_f32 v[132:133], v[136:137], v[132:133]
	v_lshlrev_b32_e32 v136, 16, v143
; __device__ __forceinline__ float bflo(unsigned w) { return __uint_as_float(w << 16); }
; __device__ __forceinline__ float bfhi(unsigned w) { return __uint_as_float(w & 0xffff0000u); }
; #define SCHED() __builtin_amdgcn_sched_barrier(0)
; template <int MODE>
; __device__ __forceinline__ void gemm_phase(const Params& p, int l, int cb, char* shm) {
;     ...
;         for (int q = 0; q < 4; ++q) {
; #pragma unroll
;           for (int i = 0; i < 4; ++i) {
;             const int so = (lrow + 8 * i) * 128 + ((lch ^ lrow) << 4);
;             *(u32x4*)(est + so) = ra[i]; *(u32x4*)(est + 4096 + so) = rb[i];
;           }
;           SCHED();
;           if (q < 3) {
; #pragma unroll
;             for (int i = 0; i < 4; ++i) { ra[i] = *(const u32x4*)(gsrc + (size_t)(32 * (q + 1) + 8 * i) * PW + PC_GA); rb[i] = *(const u32x4*)(gsrc + (size_t)(32 * (q + 1) + 8 * i) * PW + PC_GB); }
;           }
;           SCHED();
; #pragma unroll
;           for (int mm = 0; mm < 2; ++mm) {
;             const int m = q * 2 + mm, row = mm * 16 + fr;
; #pragma unroll
;             for (int n = 0; n < 4; ++n) {
;               const int off = row * 128 + (((n * 2 + (fq >> 1)) ^ (row & 7)) << 4) + (fq & 1) * 8;
;               const u32x2 ga = *(const u32x2*)(est + off), gb = *(const u32x2*)(est + 4096 + off);
;               acc[m][n][0] *= bflo(ga[0]) * __builtin_amdgcn_rcpf(fmaxf(bflo(gb[0]), 1e-30f));
;               acc[m][n][1] *= bfhi(ga[0]) * __builtin_amdgcn_rcpf(fmaxf(bfhi(gb[0]), 1e-30f));
;               acc[m][n][2] *= bflo(ga[1]) * __builtin_amdgcn_rcpf(fmaxf(bflo(gb[1]), 1e-30f));
;               acc[m][n][3] *= bfhi(ga[1]) * __builtin_amdgcn_rcpf(fmaxf(bfhi(gb[1]), 1e-30f));
;             }
;           }
	v_and_b32_e32 v137, 0xffff0000, v143
	v_max_f32_e32 v136, v136, v136
	v_max_f32_e32 v137, v137, v137
	v_max_f32_e32 v136, 0xda24260, v136
	v_max_f32_e32 v137, 0xda24260, v137
	v_rcp_f32_e32 v136, v136
	v_rcp_f32_e32 v137, v137
	v_pk_mul_f32 v[94:95], v[94:95], v[132:133]
	v_lshlrev_b32_e32 v132, 16, v139
	v_and_b32_e32 v133, 0xffff0000, v139
	v_pk_mul_f32 v[132:133], v[136:137], v[132:133]
	v_lshlrev_b32_e32 v136, 16, v134
	v_and_b32_e32 v134, 0xffff0000, v134
	v_pk_mul_f32 v[96:97], v[96:97], v[132:133]
	v_lshlrev_b32_e32 v132, 16, v130
	v_and_b32_e32 v133, 0xffff0000, v130
	v_lshlrev_b32_e32 v130, 16, v135
	v_max_f32_e32 v134, v134, v134
	v_max_f32_e32 v130, v130, v130
	v_max_f32_e32 v134, 0xda24260, v134
	v_max_f32_e32 v130, 0xda24260, v130
	v_rcp_f32_e32 v137, v134
	v_rcp_f32_e32 v134, v130
	v_and_b32_e32 v130, 0xffff0000, v135
	v_max_f32_e32 v136, v136, v136
	v_max_f32_e32 v130, v130, v130
	v_max_f32_e32 v148, 0xda24260, v148
	v_max_f32_e32 v144, 0xda24260, v144
	v_max_f32_e32 v136, 0xda24260, v136
	v_max_f32_e32 v130, 0xda24260, v130
	v_rcp_f32_e32 v148, v148
	v_rcp_f32_e32 v144, v144
	v_rcp_f32_e32 v136, v136
	v_rcp_f32_e32 v135, v130
	v_lshlrev_b32_e32 v130, 16, v131
	v_and_b32_e32 v131, 0xffff0000, v131
	v_pk_mul_f32 v[146:147], v[148:149], v[146:147]
	v_pk_mul_f32 v[140:141], v[144:145], v[140:141]
	v_pk_mul_f32 v[132:133], v[136:137], v[132:133]
	v_pk_mul_f32 v[130:131], v[134:135], v[130:131]
	v_pk_mul_f32 v[122:123], v[122:123], v[146:147]
	v_pk_mul_f32 v[126:127], v[126:127], v[140:141]
	v_pk_mul_f32 v[86:87], v[86:87], v[132:133]
	v_pk_mul_f32 v[88:89], v[88:89], v[130:131]
	ds_read2st64_b64 v[130:133], v244 offset1:4
	ds_read2st64_b64 v[134:137], v244 offset0:8 offset1:12
	s_waitcnt lgkmcnt(1)
	v_lshlrev_b32_e32 v140, 16, v130
	s_waitcnt lgkmcnt(0)
	v_lshlrev_b32_e32 v138, 16, v134
	v_and_b32_e32 v134, 0xffff0000, v134
	v_max_f32_e32 v138, v138, v138
	v_max_f32_e32 v134, v134, v134
	v_max_f32_e32 v138, 0xda24260, v138
	v_max_f32_e32 v134, 0xda24260, v134
	v_and_b32_e32 v141, 0xffff0000, v130
	v_lshlrev_b32_e32 v130, 16, v135
	v_rcp_f32_e32 v138, v138
	v_rcp_f32_e32 v139, v134
	v_max_f32_e32 v130, v130, v130
	v_max_f32_e32 v130, 0xda24260, v130
	v_rcp_f32_e32 v134, v130
	v_and_b32_e32 v130, 0xffff0000, v135
	v_max_f32_e32 v130, v130, v130
	v_pk_mul_f32 v[138:139], v[138:139], v[140:141]
	v_max_f32_e32 v130, 0xda24260, v130
	v_pk_mul_f32 v[78:79], v[78:79], v[138:139]
	v_rcp_f32_e32 v135, v130
	ds_read2st64_b64 v[138:141], v245 offset1:4
	ds_read2st64_b64 v[144:147], v245 offset0:8 offset1:12
	v_lshlrev_b32_e32 v130, 16, v131
	v_and_b32_e32 v131, 0xffff0000, v131
	v_pk_mul_f32 v[130:131], v[134:135], v[130:131]
	s_waitcnt lgkmcnt(1)
	v_lshlrev_b32_e32 v134, 16, v138
	v_pk_mul_f32 v[80:81], v[80:81], v[130:131]
	s_waitcnt lgkmcnt(0)
	v_lshlrev_b32_e32 v130, 16, v144
	v_and_b32_e32 v131, 0xffff0000, v144
	v_max_f32_e32 v130, v130, v130
	v_max_f32_e32 v131, v131, v131
	v_max_f32_e32 v130, 0xda24260, v130
	v_max_f32_e32 v131, 0xda24260, v131
	v_rcp_f32_e32 v130, v130
	v_rcp_f32_e32 v131, v131
	v_and_b32_e32 v135, 0xffff0000, v138
	v_pk_mul_f32 v[130:131], v[130:131], v[134:135]
	s_nop 0
	v_pk_mul_f32 v[66:67], v[66:67], v[130:131]
	v_lshlrev_b32_e32 v130, 16, v145
	v_and_b32_e32 v131, 0xffff0000, v145
	v_max_f32_e32 v130, v130, v130
	v_max_f32_e32 v131, v131, v131
	v_max_f32_e32 v130, 0xda24260, v130
	v_max_f32_e32 v131, 0xda24260, v131
	v_rcp_f32_e32 v130, v130
	v_rcp_f32_e32 v131, v131
	ds_read2st64_b64 v[142:145], v246 offset1:4
	ds_read2st64_b64 v[150:153], v246 offset0:8 offset1:12
	v_lshlrev_b32_e32 v134, 16, v139
	v_and_b32_e32 v135, 0xffff0000, v139
	v_pk_mul_f32 v[130:131], v[130:131], v[134:135]
	s_waitcnt lgkmcnt(1)
	v_lshlrev_b32_e32 v134, 16, v142
	v_pk_mul_f32 v[68:69], v[68:69], v[130:131]
	s_waitcnt lgkmcnt(0)
	v_lshlrev_b32_e32 v130, 16, v150
	v_and_b32_e32 v131, 0xffff0000, v150
	v_max_f32_e32 v130, v130, v130
	v_max_f32_e32 v131, v131, v131
	v_max_f32_e32 v130, 0xda24260, v130
	v_max_f32_e32 v131, 0xda24260, v131
	v_rcp_f32_e32 v130, v130
	v_rcp_f32_e32 v131, v131
	v_and_b32_e32 v135, 0xffff0000, v142
	v_pk_mul_f32 v[130:131], v[130:131], v[134:135]
	s_nop 0
	v_pk_mul_f32 v[58:59], v[58:59], v[130:131]
	v_lshlrev_b32_e32 v130, 16, v151
	v_and_b32_e32 v131, 0xffff0000, v151
	v_max_f32_e32 v130, v130, v130
	v_max_f32_e32 v131, v131, v131
	v_max_f32_e32 v130, 0xda24260, v130
	v_max_f32_e32 v131, 0xda24260, v131
	v_rcp_f32_e32 v130, v130
	v_rcp_f32_e32 v131, v131
	ds_read2st64_b64 v[148:151], v236 offset1:4
	ds_read2st64_b64 v[154:157], v236 offset0:8 offset1:12
	v_lshlrev_b32_e32 v134, 16, v143
	v_and_b32_e32 v135, 0xffff0000, v143
	v_pk_mul_f32 v[130:131], v[130:131], v[134:135]
	s_waitcnt lgkmcnt(1)
	v_lshlrev_b32_e32 v134, 16, v148
	v_pk_mul_f32 v[60:61], v[60:61], v[130:131]
	s_waitcnt lgkmcnt(0)
; __device__ __forceinline__ float bflo(unsigned w) { return __uint_as_float(w << 16); }
; __device__ __forceinline__ float bfhi(unsigned w) { return __uint_as_float(w & 0xffff0000u); }
; #define SCHED() __builtin_amdgcn_sched_barrier(0)
; #define KLOOP(K0, K1) _Pragma("unroll 1") for (int kt = (K0); kt < (K1); ++kt) { const int cur = kt & 1;        \
;       if (kt + 1 < 16) GLDS_STAGE(cur ^ 1, kt + 1);                                                               \
;       const char* ab = a0 + cur * STAGE_B; const char* bb = b0 + cur * STAGE_B;                                  \
;       COMPUTE(ab, bb); WAIT_V(0); __syncthreads(); }
; template <int MODE>
; __device__ __forceinline__ void gemm_phase(const Params& p, int l, int cb, char* shm) {
;     ...
; #pragma unroll
;           for (int mm = 0; mm < 2; ++mm) {
;             const int m = q * 2 + mm, row = mm * 16 + fr;
; #pragma unroll
;             for (int n = 0; n < 4; ++n) {
;               const int off = row * 128 + (((n * 2 + (fq >> 1)) ^ (row & 7)) << 4) + (fq & 1) * 8;
;               const u32x2 ga = *(const u32x2*)(est + off), gb = *(const u32x2*)(est + 4096 + off);
;               acc[m][n][0] *= bflo(ga[0]) * __builtin_amdgcn_rcpf(fmaxf(bflo(gb[0]), 1e-30f));
;               acc[m][n][1] *= bfhi(ga[0]) * __builtin_amdgcn_rcpf(fmaxf(bfhi(gb[0]), 1e-30f));
;               acc[m][n][2] *= bflo(ga[1]) * __builtin_amdgcn_rcpf(fmaxf(bflo(gb[1]), 1e-30f));
;               acc[m][n][3] *= bfhi(ga[1]) * __builtin_amdgcn_rcpf(fmaxf(bfhi(gb[1]), 1e-30f));
;             }
;           }
;           SCHED();
;         }
;       }
;       __syncthreads();
;       SCHED();
;       fr = fr0; fq = fq0;
;       KLOOP(8, 16);
	v_lshlrev_b32_e32 v130, 16, v154
	v_and_b32_e32 v131, 0xffff0000, v154
	v_max_f32_e32 v130, v130, v130
	v_max_f32_e32 v131, v131, v131
	v_max_f32_e32 v130, 0xda24260, v130
	v_max_f32_e32 v131, 0xda24260, v131
	v_rcp_f32_e32 v130, v130
	v_rcp_f32_e32 v131, v131
	v_and_b32_e32 v135, 0xffff0000, v148
	v_pk_mul_f32 v[130:131], v[130:131], v[134:135]
	s_nop 0
	v_pk_mul_f32 v[50:51], v[50:51], v[130:131]
	v_lshlrev_b32_e32 v130, 16, v155
	v_and_b32_e32 v131, 0xffff0000, v155
	v_max_f32_e32 v130, v130, v130
	v_max_f32_e32 v131, v131, v131
	v_max_f32_e32 v130, 0xda24260, v130
	v_max_f32_e32 v131, 0xda24260, v131
	v_rcp_f32_e32 v130, v130
	v_rcp_f32_e32 v131, v131
	v_lshlrev_b32_e32 v134, 16, v149
	v_and_b32_e32 v135, 0xffff0000, v149
	v_pk_mul_f32 v[130:131], v[130:131], v[134:135]
	s_nop 0
	v_pk_mul_f32 v[52:53], v[52:53], v[130:131]
	v_lshlrev_b32_e32 v130, 16, v136
	v_and_b32_e32 v131, 0xffff0000, v136
	v_max_f32_e32 v130, v130, v130
	v_max_f32_e32 v131, v131, v131
	v_max_f32_e32 v130, 0xda24260, v130
	v_max_f32_e32 v131, 0xda24260, v131
	v_rcp_f32_e32 v130, v130
	v_rcp_f32_e32 v131, v131
	v_lshlrev_b32_e32 v134, 16, v132
	v_and_b32_e32 v135, 0xffff0000, v132
	v_lshlrev_b32_e32 v132, 16, v133
	v_pk_mul_f32 v[130:131], v[130:131], v[134:135]
	v_and_b32_e32 v133, 0xffff0000, v133
	v_pk_mul_f32 v[46:47], v[46:47], v[130:131]
	v_lshlrev_b32_e32 v130, 16, v137
	v_and_b32_e32 v131, 0xffff0000, v137
	v_max_f32_e32 v130, v130, v130
	v_max_f32_e32 v131, v131, v131
	v_max_f32_e32 v130, 0xda24260, v130
	v_max_f32_e32 v131, 0xda24260, v131
	v_rcp_f32_e32 v130, v130
	v_rcp_f32_e32 v131, v131
	s_nop 0
	v_pk_mul_f32 v[130:131], v[130:131], v[132:133]
	s_nop 0
	v_pk_mul_f32 v[48:49], v[48:49], v[130:131]
	v_lshlrev_b32_e32 v130, 16, v146
	v_and_b32_e32 v131, 0xffff0000, v146
	v_max_f32_e32 v130, v130, v130
	v_max_f32_e32 v131, v131, v131
	v_max_f32_e32 v130, 0xda24260, v130
	v_max_f32_e32 v131, 0xda24260, v131
	v_rcp_f32_e32 v130, v130
	v_rcp_f32_e32 v131, v131
	v_lshlrev_b32_e32 v132, 16, v140
	v_and_b32_e32 v133, 0xffff0000, v140
	v_pk_mul_f32 v[130:131], v[130:131], v[132:133]
	s_nop 0
	v_pk_mul_f32 v[38:39], v[38:39], v[130:131]
	v_lshlrev_b32_e32 v130, 16, v147
	v_and_b32_e32 v131, 0xffff0000, v147
	v_max_f32_e32 v130, v130, v130
	v_max_f32_e32 v131, v131, v131
	v_max_f32_e32 v130, 0xda24260, v130
	v_max_f32_e32 v131, 0xda24260, v131
	v_rcp_f32_e32 v130, v130
	v_rcp_f32_e32 v131, v131
	v_lshlrev_b32_e32 v132, 16, v141
	v_and_b32_e32 v133, 0xffff0000, v141
	v_pk_mul_f32 v[130:131], v[130:131], v[132:133]
	s_nop 0
	v_pk_mul_f32 v[40:41], v[40:41], v[130:131]
	v_lshlrev_b32_e32 v130, 16, v152
	v_and_b32_e32 v131, 0xffff0000, v152
	v_max_f32_e32 v130, v130, v130
	v_max_f32_e32 v131, v131, v131
	v_max_f32_e32 v130, 0xda24260, v130
	v_max_f32_e32 v131, 0xda24260, v131
	v_rcp_f32_e32 v130, v130
	v_rcp_f32_e32 v131, v131
	v_lshlrev_b32_e32 v132, 16, v144
	v_and_b32_e32 v133, 0xffff0000, v144
	v_pk_mul_f32 v[130:131], v[130:131], v[132:133]
	s_nop 0
	v_pk_mul_f32 v[30:31], v[30:31], v[130:131]
	v_lshlrev_b32_e32 v130, 16, v153
	v_and_b32_e32 v131, 0xffff0000, v153
	v_max_f32_e32 v130, v130, v130
	v_max_f32_e32 v131, v131, v131
	v_max_f32_e32 v130, 0xda24260, v130
	v_max_f32_e32 v131, 0xda24260, v131
	v_rcp_f32_e32 v130, v130
	v_rcp_f32_e32 v131, v131
	v_lshlrev_b32_e32 v132, 16, v145
	v_and_b32_e32 v133, 0xffff0000, v145
	v_pk_mul_f32 v[130:131], v[130:131], v[132:133]
	s_nop 0
	v_pk_mul_f32 v[32:33], v[32:33], v[130:131]
	v_lshlrev_b32_e32 v130, 16, v156
	v_and_b32_e32 v131, 0xffff0000, v156
	v_max_f32_e32 v130, v130, v130
	v_max_f32_e32 v131, v131, v131
	v_max_f32_e32 v130, 0xda24260, v130
	v_max_f32_e32 v131, 0xda24260, v131
	v_rcp_f32_e32 v130, v130
	v_rcp_f32_e32 v131, v131
	v_lshlrev_b32_e32 v132, 16, v150
	v_and_b32_e32 v133, 0xffff0000, v150
	v_pk_mul_f32 v[130:131], v[130:131], v[132:133]
	s_nop 0
	v_pk_mul_f32 v[22:23], v[22:23], v[130:131]
	v_lshlrev_b32_e32 v130, 16, v157
	v_and_b32_e32 v131, 0xffff0000, v157
	v_max_f32_e32 v130, v130, v130
	v_max_f32_e32 v131, v131, v131
	v_max_f32_e32 v130, 0xda24260, v130
	v_max_f32_e32 v131, 0xda24260, v131
	v_rcp_f32_e32 v130, v130
	v_rcp_f32_e32 v131, v131
	v_lshlrev_b32_e32 v132, 16, v151
	v_and_b32_e32 v133, 0xffff0000, v151
	v_pk_mul_f32 v[130:131], v[130:131], v[132:133]
	s_nop 0
	v_pk_mul_f32 v[24:25], v[24:25], v[130:131]
	s_barrier
	v_lshl_add_u64 v[130:131], v[214:215], 0, s[14:15]
	v_lshl_add_u64 v[132:133], v[216:217], 0, s[14:15]
	v_lshl_add_u64 v[134:135], v[218:219], 0, s[14:15]
	v_lshl_add_u64 v[136:137], v[220:221], 0, s[14:15]
	v_lshl_add_u64 v[138:139], v[222:223], 0, s[16:17]
	v_lshl_add_u64 v[140:141], v[224:225], 0, s[16:17]
	v_lshl_add_u64 v[142:143], v[226:227], 0, s[16:17]
	v_lshl_add_u64 v[144:145], v[228:229], 0, s[16:17]
	s_mov_b32 s7, 0x80000
	s_mov_b64 s[0:1], 0
	s_branch .LBB0_593

; #define KLOOP(K0, K1) _Pragma("unroll 1") for (int kt = (K0); kt < (K1); ++kt) { const int cur = kt & 1;        \
;       if (kt + 1 < 16) GLDS_STAGE(cur ^ 1, kt + 1);                                                               \
;       const char* ab = a0 + cur * STAGE_B; const char* bb = b0 + cur * STAGE_B;                                  \
;       COMPUTE(ab, bb); WAIT_V(0); __syncthreads(); }
; template <int MODE>
; __device__ __forceinline__ void gemm_phase(const Params& p, int l, int cb, char* shm) {
;     ...
;       KLOOP(8, 16);
.LBB0_593:
	s_cmpk_eq_i32 s0, 0x380
	s_mov_b32 s14, 0x10000
	s_cbranch_scc1 .LBB0_592
	s_and_b32 s14, s7, 0x10000
	s_xor_b32 s15, s14, 0x10000
	s_add_i32 s15, s20, s15
	s_add_i32 s16, s15, 0x8000
	v_add_u32_e32 v179, s14, v237
	v_add_u32_e32 v178, s14, v253
	ds_read_b128 v[146:149], v179 offset:32768
	ds_read_b128 v[150:153], v179 offset:34816
	ds_read_b128 v[154:157], v179 offset:36864
	ds_read_b128 v[158:161], v179 offset:38912
	ds_read_b128 v[162:165], v178
	ds_read_b128 v[166:169], v178 offset:2048
	v_add_u32_e32 v232, v178, v252
	ds_read_b128 v[170:173], v178 offset:4096
	ds_read_b128 v[174:177], v178 offset:6144
	v_lshl_add_u64 v[186:187], v[130:131], 0, s[0:1]
	s_mov_b32 m0, s15
	s_nop 0
	global_load_lds_dwordx4 v[186:187], off
	v_lshl_add_u64 v[186:187], v[138:139], 0, s[0:1]
	s_mov_b32 m0, s16
	s_nop 0
	global_load_lds_dwordx4 v[186:187], off
	s_waitcnt lgkmcnt(0)
	v_mfma_f32_16x16x32_bf16 v[2:5], v[146:149], v[162:165], v[2:5]
	v_mfma_f32_16x16x32_bf16 v[6:9], v[150:153], v[162:165], v[6:9]
	v_lshl_add_u64 v[186:187], v[132:133], 0, s[0:1]
	s_add_i32 m0, s15, 0x2000
	s_nop 0
	global_load_lds_dwordx4 v[186:187], off
	v_mfma_f32_16x16x32_bf16 v[10:13], v[154:157], v[162:165], v[10:13]
	v_mfma_f32_16x16x32_bf16 v[14:17], v[158:161], v[162:165], v[14:17]
	v_mfma_f32_16x16x32_bf16 v[18:21], v[146:149], v[166:169], v[18:21]
	v_mfma_f32_16x16x32_bf16 v[26:29], v[150:153], v[166:169], v[26:29]
	v_lshl_add_u64 v[186:187], v[140:141], 0, s[0:1]
	s_add_i32 m0, s15, 0xa000
	s_nop 0
	global_load_lds_dwordx4 v[186:187], off
	v_mfma_f32_16x16x32_bf16 v[34:37], v[154:157], v[166:169], v[34:37]
	v_mfma_f32_16x16x32_bf16 v[42:45], v[158:161], v[166:169], v[42:45]
	ds_read_b128 v[162:165], v178 offset:8192
	ds_read_b128 v[166:169], v178 offset:10240
	v_mfma_f32_16x16x32_bf16 v[54:57], v[146:149], v[170:173], v[54:57]
	v_mfma_f32_16x16x32_bf16 v[62:65], v[150:153], v[170:173], v[62:65]
	v_lshl_add_u64 v[186:187], v[134:135], 0, s[0:1]
	s_add_i32 m0, s15, 0x4000
	s_nop 0
	global_load_lds_dwordx4 v[186:187], off
	v_mfma_f32_16x16x32_bf16 v[70:73], v[154:157], v[170:173], v[70:73]
	v_mfma_f32_16x16x32_bf16 v[74:77], v[158:161], v[170:173], v[74:77]
	v_mfma_f32_16x16x32_bf16 v[82:85], v[146:149], v[174:177], v[82:85]
	v_mfma_f32_16x16x32_bf16 v[90:93], v[150:153], v[174:177], v[90:93]
	v_lshl_add_u64 v[186:187], v[142:143], 0, s[0:1]
	s_add_i32 m0, s15, 0xc000
	s_nop 0
	global_load_lds_dwordx4 v[186:187], off
	v_mfma_f32_16x16x32_bf16 v[102:105], v[154:157], v[174:177], v[102:105]
	v_mfma_f32_16x16x32_bf16 v[114:117], v[158:161], v[174:177], v[114:117]
	ds_read_b128 v[170:173], v178 offset:12288
	ds_read_b128 v[174:177], v178 offset:14336
	s_waitcnt lgkmcnt(0)
	v_mfma_f32_16x16x32_bf16 v[86:89], v[146:149], v[162:165], v[86:89]
	v_add_u32_e32 v182, v179, v252
	v_mfma_f32_16x16x32_bf16 v[94:97], v[150:153], v[162:165], v[94:97]
	v_lshl_add_u64 v[186:187], v[136:137], 0, s[0:1]
	s_add_i32 m0, s15, 0x6000
	s_nop 0
	global_load_lds_dwordx4 v[186:187], off
	v_mfma_f32_16x16x32_bf16 v[106:109], v[154:157], v[162:165], v[106:109]
	v_mfma_f32_16x16x32_bf16 v[118:121], v[158:161], v[162:165], v[118:121]
	v_mfma_f32_16x16x32_bf16 v[126:129], v[146:149], v[166:169], v[126:129]
	v_mfma_f32_16x16x32_bf16 v[122:125], v[150:153], v[166:169], v[122:125]
	v_lshl_add_u64 v[186:187], v[144:145], 0, s[0:1]
	s_add_i32 m0, s15, 0xe000
	s_nop 0
	global_load_lds_dwordx4 v[186:187], off
	v_mfma_f32_16x16x32_bf16 v[110:113], v[154:157], v[166:169], v[110:113]
	v_mfma_f32_16x16x32_bf16 v[98:101], v[158:161], v[166:169], v[98:101]
	ds_read_b128 v[162:165], v182 offset:32768
	ds_read_b128 v[166:169], v182 offset:34816
	ds_read_b128 v[178:181], v182 offset:36864
	ds_read_b128 v[182:185], v182 offset:38912
	ds_read_b128 v[186:189], v232
	ds_read_b128 v[198:201], v232 offset:2048
	v_mfma_f32_16x16x32_bf16 v[78:81], v[146:149], v[170:173], v[78:81]
	v_mfma_f32_16x16x32_bf16 v[66:69], v[150:153], v[170:173], v[66:69]
	v_mfma_f32_16x16x32_bf16 v[58:61], v[154:157], v[170:173], v[58:61]
	v_mfma_f32_16x16x32_bf16 v[50:53], v[158:161], v[170:173], v[50:53]
	v_mfma_f32_16x16x32_bf16 v[46:49], v[146:149], v[174:177], v[46:49]
	v_mfma_f32_16x16x32_bf16 v[38:41], v[150:153], v[174:177], v[38:41]
	v_mfma_f32_16x16x32_bf16 v[30:33], v[154:157], v[174:177], v[30:33]
	v_mfma_f32_16x16x32_bf16 v[22:25], v[158:161], v[174:177], v[22:25]
	ds_read_b128 v[146:149], v232 offset:4096
	ds_read_b128 v[150:153], v232 offset:6144
	s_waitcnt lgkmcnt(0)
	v_mfma_f32_16x16x32_bf16 v[2:5], v[162:165], v[186:189], v[2:5]
	v_mfma_f32_16x16x32_bf16 v[6:9], v[166:169], v[186:189], v[6:9]
	v_mfma_f32_16x16x32_bf16 v[10:13], v[178:181], v[186:189], v[10:13]
	v_mfma_f32_16x16x32_bf16 v[14:17], v[182:185], v[186:189], v[14:17]
	v_mfma_f32_16x16x32_bf16 v[18:21], v[162:165], v[198:201], v[18:21]
	v_mfma_f32_16x16x32_bf16 v[26:29], v[166:169], v[198:201], v[26:29]
	v_mfma_f32_16x16x32_bf16 v[34:37], v[178:181], v[198:201], v[34:37]
	v_mfma_f32_16x16x32_bf16 v[42:45], v[182:185], v[198:201], v[42:45]
	ds_read_b128 v[154:157], v232 offset:8192
	ds_read_b128 v[158:161], v232 offset:10240
	v_mfma_f32_16x16x32_bf16 v[54:57], v[162:165], v[146:149], v[54:57]
	v_mfma_f32_16x16x32_bf16 v[62:65], v[166:169], v[146:149], v[62:65]
	v_mfma_f32_16x16x32_bf16 v[70:73], v[178:181], v[146:149], v[70:73]
	v_mfma_f32_16x16x32_bf16 v[74:77], v[182:185], v[146:149], v[74:77]
	v_mfma_f32_16x16x32_bf16 v[82:85], v[162:165], v[150:153], v[82:85]
	v_mfma_f32_16x16x32_bf16 v[90:93], v[166:169], v[150:153], v[90:93]
	v_mfma_f32_16x16x32_bf16 v[102:105], v[178:181], v[150:153], v[102:105]
	v_mfma_f32_16x16x32_bf16 v[114:117], v[182:185], v[150:153], v[114:117]
	ds_read_b128 v[146:149], v232 offset:12288
	ds_read_b128 v[150:153], v232 offset:14336
	s_waitcnt lgkmcnt(0)
	v_mfma_f32_16x16x32_bf16 v[86:89], v[162:165], v[154:157], v[86:89]
	v_mfma_f32_16x16x32_bf16 v[94:97], v[166:169], v[154:157], v[94:97]
	v_mfma_f32_16x16x32_bf16 v[106:109], v[178:181], v[154:157], v[106:109]
	v_mfma_f32_16x16x32_bf16 v[118:121], v[182:185], v[154:157], v[118:121]
	v_mfma_f32_16x16x32_bf16 v[126:129], v[162:165], v[158:161], v[126:129]
	v_mfma_f32_16x16x32_bf16 v[122:125], v[166:169], v[158:161], v[122:125]
	v_mfma_f32_16x16x32_bf16 v[110:113], v[178:181], v[158:161], v[110:113]
	v_mfma_f32_16x16x32_bf16 v[98:101], v[182:185], v[158:161], v[98:101]
	v_mfma_f32_16x16x32_bf16 v[78:81], v[162:165], v[146:149], v[78:81]
	v_mfma_f32_16x16x32_bf16 v[66:69], v[166:169], v[146:149], v[66:69]
	v_mfma_f32_16x16x32_bf16 v[58:61], v[178:181], v[146:149], v[58:61]
	v_mfma_f32_16x16x32_bf16 v[50:53], v[182:185], v[146:149], v[50:53]
	v_mfma_f32_16x16x32_bf16 v[46:49], v[162:165], v[150:153], v[46:49]
	v_mfma_f32_16x16x32_bf16 v[38:41], v[166:169], v[150:153], v[38:41]
	v_mfma_f32_16x16x32_bf16 v[30:33], v[178:181], v[150:153], v[30:33]
	v_mfma_f32_16x16x32_bf16 v[22:25], v[182:185], v[150:153], v[22:25]
	s_add_i32 s7, s7, 0x10000
	s_waitcnt vmcnt(0)
	s_add_u32 s0, s0, 0x80
	s_addc_u32 s1, s1, 0
	s_cmpk_eq_i32 s0, 0x400
	s_waitcnt vmcnt(0)
	s_barrier
	s_cbranch_scc1 .LBB0_595
	s_branch .LBB0_593

; #define KLOOP(K0, K1) _Pragma("unroll 1") for (int kt = (K0); kt < (K1); ++kt) { const int cur = kt & 1;        \
;       if (kt + 1 < 16) GLDS_STAGE(cur ^ 1, kt + 1);                                                               \
;       const char* ab = a0 + cur * STAGE_B; const char* bb = b0 + cur * STAGE_B;                                  \
;       COMPUTE(ab, bb); WAIT_V(0); __syncthreads(); }
; template <int MODE>
; __device__ __forceinline__ void gemm_phase(const Params& p, int l, int cb, char* shm) {
;     ...
;       KLOOP(0, 16);
.LBB0_639:
	s_cmpk_eq_i32 s10, 0x780
	s_mov_b32 s12, 0x10000
	s_cbranch_scc1 .LBB0_638
	s_and_b32 s12, s9, 0x10000
	s_xor_b32 s13, s12, 0x10000
	s_add_i32 s13, s18, s13
	s_add_i32 s14, s13, 0x8000
	v_add_u32_e32 v171, s12, v176
	v_add_u32_e32 v170, s12, v175
	ds_read_b128 v[180:183], v171 offset:32768
	ds_read_b128 v[184:187], v171 offset:34816
	ds_read_b128 v[188:191], v171 offset:36864
	ds_read_b128 v[192:195], v171 offset:38912
	ds_read_b128 v[196:199], v170
	ds_read_b128 v[200:203], v170 offset:2048
	v_add_u32_e32 v179, v170, v174
	ds_read_b128 v[204:207], v170 offset:4096
	ds_read_b128 v[208:211], v170 offset:6144
	v_lshl_add_u64 v[252:253], v[130:131], 0, s[10:11]
	s_mov_b32 m0, s13
	s_nop 0
	global_load_lds_dwordx4 v[252:253], off
	v_lshl_add_u64 v[252:253], v[138:139], 0, s[10:11]
	s_mov_b32 m0, s14
	s_nop 0
	global_load_lds_dwordx4 v[252:253], off
	s_waitcnt lgkmcnt(0)
	v_mfma_f32_16x16x32_bf16 v[126:129], v[180:183], v[196:199], v[126:129]
	v_mfma_f32_16x16x32_bf16 v[122:125], v[184:187], v[196:199], v[122:125]
	v_lshl_add_u64 v[252:253], v[132:133], 0, s[10:11]
	s_add_i32 m0, s13, 0x2000
	s_nop 0
	global_load_lds_dwordx4 v[252:253], off
	v_mfma_f32_16x16x32_bf16 v[118:121], v[188:191], v[196:199], v[118:121]
	v_mfma_f32_16x16x32_bf16 v[114:117], v[192:195], v[196:199], v[114:117]
	v_mfma_f32_16x16x32_bf16 v[110:113], v[180:183], v[200:203], v[110:113]
	v_mfma_f32_16x16x32_bf16 v[106:109], v[184:187], v[200:203], v[106:109]
	v_lshl_add_u64 v[252:253], v[140:141], 0, s[10:11]
	s_add_i32 m0, s13, 0xa000
	s_nop 0
	global_load_lds_dwordx4 v[252:253], off
	v_mfma_f32_16x16x32_bf16 v[102:105], v[188:191], v[200:203], v[102:105]
	v_mfma_f32_16x16x32_bf16 v[98:101], v[192:195], v[200:203], v[98:101]
	ds_read_b128 v[196:199], v170 offset:8192
	ds_read_b128 v[200:203], v170 offset:10240
	v_mfma_f32_16x16x32_bf16 v[94:97], v[180:183], v[204:207], v[94:97]
	v_mfma_f32_16x16x32_bf16 v[90:93], v[184:187], v[204:207], v[90:93]
	v_lshl_add_u64 v[252:253], v[134:135], 0, s[10:11]
	s_add_i32 m0, s13, 0x4000
	s_nop 0
	global_load_lds_dwordx4 v[252:253], off
	v_mfma_f32_16x16x32_bf16 v[86:89], v[188:191], v[204:207], v[86:89]
	v_mfma_f32_16x16x32_bf16 v[82:85], v[192:195], v[204:207], v[82:85]
	v_mfma_f32_16x16x32_bf16 v[78:81], v[180:183], v[208:211], v[78:81]
	v_mfma_f32_16x16x32_bf16 v[74:77], v[184:187], v[208:211], v[74:77]
	v_lshl_add_u64 v[252:253], v[142:143], 0, s[10:11]
	s_add_i32 m0, s13, 0xc000
	s_nop 0
	global_load_lds_dwordx4 v[252:253], off
	v_mfma_f32_16x16x32_bf16 v[70:73], v[188:191], v[208:211], v[70:73]
	v_mfma_f32_16x16x32_bf16 v[66:69], v[192:195], v[208:211], v[66:69]
	ds_read_b128 v[204:207], v170 offset:12288
	ds_read_b128 v[208:211], v170 offset:14336
	s_waitcnt lgkmcnt(0)
	v_mfma_f32_16x16x32_bf16 v[42:45], v[180:183], v[196:199], v[42:45]
	v_add_u32_e32 v170, v171, v174
	v_mfma_f32_16x16x32_bf16 v[30:33], v[184:187], v[196:199], v[30:33]
	v_lshl_add_u64 v[252:253], v[136:137], 0, s[10:11]
	s_add_i32 m0, s13, 0x6000
	s_nop 0
	global_load_lds_dwordx4 v[252:253], off
	v_mfma_f32_16x16x32_bf16 v[14:17], v[188:191], v[196:199], v[14:17]
	v_mfma_f32_16x16x32_bf16 v[2:5], v[192:195], v[196:199], v[2:5]
	v_mfma_f32_16x16x32_bf16 v[62:65], v[180:183], v[200:203], v[62:65]
	v_mfma_f32_16x16x32_bf16 v[58:61], v[184:187], v[200:203], v[58:61]
	v_lshl_add_u64 v[252:253], v[144:145], 0, s[10:11]
	s_add_i32 m0, s13, 0xe000
	s_nop 0
	global_load_lds_dwordx4 v[252:253], off
	v_mfma_f32_16x16x32_bf16 v[54:57], v[188:191], v[200:203], v[54:57]
	v_mfma_f32_16x16x32_bf16 v[50:53], v[192:195], v[200:203], v[50:53]
	ds_read_b128 v[196:199], v170 offset:32768
	ds_read_b128 v[200:203], v170 offset:34816
	ds_read_b128 v[212:215], v170 offset:36864
	ds_read_b128 v[216:219], v170 offset:38912
	ds_read_b128 v[220:223], v179
	ds_read_b128 v[224:227], v179 offset:2048
	v_mfma_f32_16x16x32_bf16 v[46:49], v[180:183], v[204:207], v[46:49]
	v_mfma_f32_16x16x32_bf16 v[38:41], v[184:187], v[204:207], v[38:41]
	v_mfma_f32_16x16x32_bf16 v[34:37], v[188:191], v[204:207], v[34:37]
	v_mfma_f32_16x16x32_bf16 v[26:29], v[192:195], v[204:207], v[26:29]
	v_mfma_f32_16x16x32_bf16 v[22:25], v[180:183], v[208:211], v[22:25]
	v_mfma_f32_16x16x32_bf16 v[18:21], v[184:187], v[208:211], v[18:21]
	v_mfma_f32_16x16x32_bf16 v[10:13], v[188:191], v[208:211], v[10:13]
	v_mfma_f32_16x16x32_bf16 v[6:9], v[192:195], v[208:211], v[6:9]
	ds_read_b128 v[180:183], v179 offset:4096
	ds_read_b128 v[184:187], v179 offset:6144
	s_waitcnt lgkmcnt(0)
	v_mfma_f32_16x16x32_bf16 v[126:129], v[196:199], v[220:223], v[126:129]
	v_mfma_f32_16x16x32_bf16 v[122:125], v[200:203], v[220:223], v[122:125]
	v_mfma_f32_16x16x32_bf16 v[118:121], v[212:215], v[220:223], v[118:121]
	v_mfma_f32_16x16x32_bf16 v[114:117], v[216:219], v[220:223], v[114:117]
	v_mfma_f32_16x16x32_bf16 v[110:113], v[196:199], v[224:227], v[110:113]
	v_mfma_f32_16x16x32_bf16 v[106:109], v[200:203], v[224:227], v[106:109]
	v_mfma_f32_16x16x32_bf16 v[102:105], v[212:215], v[224:227], v[102:105]
	v_mfma_f32_16x16x32_bf16 v[98:101], v[216:219], v[224:227], v[98:101]
	ds_read_b128 v[188:191], v179 offset:8192
	ds_read_b128 v[192:195], v179 offset:10240
	v_mfma_f32_16x16x32_bf16 v[94:97], v[196:199], v[180:183], v[94:97]
	v_mfma_f32_16x16x32_bf16 v[90:93], v[200:203], v[180:183], v[90:93]
	v_mfma_f32_16x16x32_bf16 v[86:89], v[212:215], v[180:183], v[86:89]
	v_mfma_f32_16x16x32_bf16 v[82:85], v[216:219], v[180:183], v[82:85]
	v_mfma_f32_16x16x32_bf16 v[78:81], v[196:199], v[184:187], v[78:81]
	v_mfma_f32_16x16x32_bf16 v[74:77], v[200:203], v[184:187], v[74:77]
	v_mfma_f32_16x16x32_bf16 v[70:73], v[212:215], v[184:187], v[70:73]
	v_mfma_f32_16x16x32_bf16 v[66:69], v[216:219], v[184:187], v[66:69]
	ds_read_b128 v[180:183], v179 offset:12288
	ds_read_b128 v[184:187], v179 offset:14336
	s_waitcnt lgkmcnt(0)
	v_mfma_f32_16x16x32_bf16 v[42:45], v[196:199], v[188:191], v[42:45]
	v_mfma_f32_16x16x32_bf16 v[30:33], v[200:203], v[188:191], v[30:33]
	v_mfma_f32_16x16x32_bf16 v[14:17], v[212:215], v[188:191], v[14:17]
	v_mfma_f32_16x16x32_bf16 v[2:5], v[216:219], v[188:191], v[2:5]
	v_mfma_f32_16x16x32_bf16 v[62:65], v[196:199], v[192:195], v[62:65]
	v_mfma_f32_16x16x32_bf16 v[58:61], v[200:203], v[192:195], v[58:61]
	v_mfma_f32_16x16x32_bf16 v[54:57], v[212:215], v[192:195], v[54:57]
	v_mfma_f32_16x16x32_bf16 v[50:53], v[216:219], v[192:195], v[50:53]
	v_mfma_f32_16x16x32_bf16 v[46:49], v[196:199], v[180:183], v[46:49]
	v_mfma_f32_16x16x32_bf16 v[38:41], v[200:203], v[180:183], v[38:41]
	v_mfma_f32_16x16x32_bf16 v[34:37], v[212:215], v[180:183], v[34:37]
	v_mfma_f32_16x16x32_bf16 v[26:29], v[216:219], v[180:183], v[26:29]
	v_mfma_f32_16x16x32_bf16 v[22:25], v[196:199], v[184:187], v[22:25]
	v_mfma_f32_16x16x32_bf16 v[18:21], v[200:203], v[184:187], v[18:21]
	v_mfma_f32_16x16x32_bf16 v[10:13], v[212:215], v[184:187], v[10:13]
	v_mfma_f32_16x16x32_bf16 v[6:9], v[216:219], v[184:187], v[6:9]
	s_add_i32 s9, s9, 0x10000
	s_waitcnt vmcnt(0)
	s_add_u32 s10, s10, 0x80
	s_addc_u32 s11, s11, 0
	s_cmpk_eq_i32 s10, 0x800
	s_waitcnt vmcnt(0)
	s_barrier
	s_cbranch_scc1 .LBB0_641
	s_branch .LBB0_639
